# attn_d: flat half-unit loop; the two staging loads past the last tile prefetch the next half-unit's K(0)/K(1)/V(0); q prefetched right after the loop
# baseline (speedup 1.0000x reference)
; DI int otid() { int t = threadIdx.x; asm volatile("" : "+v"(t)); return t; }
; DI void phase_attn_d(const Params& p, LAS unsigned char* lds) {
;     const bf16_t* qkv = (const bf16_t*)(p.ws + ACT); const bf16_t* lat = (const bf16_t*)(p.ws + LAT); const bf16_t* gb = (const bf16_t*)(p.ws + HBUF);
;     bf16_t* y = (bf16_t*)(p.ws + HBUF);
;     for (int pr = blockIdx.x; pr < 512; pr += gridDim.x) {
;         const int bi = pr & 255, bh = (gridDim.x == 256) ? (bi & 7) + 8 * (bi >> 6) + 32 * (pr >> 8) : pr >> 3, j = (gridDim.x == 256) ? (bi >> 3) & 7 : pr & 7, b = bh >> 4, h = bh & 15;
;         for (int half = 0; half < 2; ++half) {
;             const int qb = half ? 15 - j : j;
;             __syncthreads();
;             const int tid = otid(), wid = tid >> 6, lane = tid & 63, l32 = lane & 31;
;             const size_t tok0 = (size_t)b * SEQ, tokq = tok0 + qb * 256 + wid * 32 + l32;
.Lad_gnskip:
	s_or_b64 exec, exec, s[66:67]
	v_add_u32_e32 v239, 108544, v239
	s_add_u32 s8, s6, 0xbf00000
	s_addc_u32 s9, s7, 0
	s_add_u32 s10, s6, 0x7f00000
	s_addc_u32 s11, s7, 0
	s_mov_b32 s14, s2
	s_mov_b32 s15, 0
	s_mov_b32 s77, 1

; DI int otid() { int t = threadIdx.x; asm volatile("" : "+v"(t)); return t; }
; template <int DQK, int KA8, int DV, bool BIAS, bool JOINT>
; DI void attn_core(LAS unsigned char* lds, const bf16_t* Qrow, const bf16_t* KpA, int ldkA, const bf16_t* KpB, int ldkB, const bf16_t* Vp, int ldv,
;                   int qb, int wid, int lane, const float* qng  , f32x16 (&O)[DV / 32]) {
;     ...
;     bf16x8 qf[DQK / 16];
; #pragma unroll
;     for (int s = 0; s < DQK / 16; ++s) qf[s] = *(const bf16x8*)(Qrow + 16 * s + 8 * hh);
; DI void phase_attn_d(const Params& p, LAS unsigned char* lds) {
;     ...
;     for (int pr = blockIdx.x; pr < 512; pr += gridDim.x) {
;         const int bi = pr & 255, bh = (gridDim.x == 256) ? (bi & 7) + 8 * (bi >> 6) + 32 * (pr >> 8) : pr >> 3, j = (gridDim.x == 256) ? (bi >> 3) & 7 : pr & 7, b = bh >> 4, h = bh & 15;
;         for (int half = 0; half < 2; ++half) {
;             const int qb = half ? 15 - j : j;
;             __syncthreads();
;             const int tid = otid(), wid = tid >> 6, lane = tid & 63, l32 = lane & 31;
;             const size_t tok0 = (size_t)b * SEQ, tokq = tok0 + qb * 256 + wid * 32 + l32;
;             f32x16 O[4];
;             attn_core<192, 16, 128, false, true>(lds, qkv + tokq * 7168 + h * 192, qkv + tok0 * 7168 + 3072 + h * 256, 7168, lat + tok0 * 1088 + 1024, 1088,
;                                            qkv + tok0 * 7168 + 3072 + h * 256 + 128, 7168, qb, wid, lane, p.in[27], O);
.Lad_decoded2:
	s_lshr_b32 s28, s58, 4
	s_and_b32 s27, s58, 15
	s_sub_i32 s58, 15, s29
	s_cmp_eq_u32 s15, 0
	s_cselect_b32 s16, s29, s58
	s_lshl_b32 s17, s16, 2
	s_add_i32 s17, s17, 4
	s_lshl_b32 s60, s16, 8
	s_lshl_b32 s58, s26, 5
	s_add_i32 s60, s60, s58
	s_mov_b32 s43, s60
	s_lshr_b32 s25, s43, 6
	s_lshl_b32 s58, s28, 12
	s_add_i32 s59, s58, s60
	s_mul_i32 s60, s59, 14336
	s_mul_hi_u32 s61, s59, 14336
	s_mul_i32 s42, s27, 384
	s_add_u32 s46, s8, s60
	s_addc_u32 s47, s9, s61
	s_add_u32 s46, s46, s42
	s_addc_u32 s47, s47, 0
	s_mul_i32 s60, s58, 14336
	s_mul_hi_u32 s61, s58, 14336
	s_lshl_b32 s42, s27, 9
	s_add_u32 s48, s8, s60
	s_addc_u32 s49, s9, s61
	s_add_u32 s48, s48, s42
	s_addc_u32 s49, s49, 0
	s_add_u32 s48, s48, 0x1800
	s_addc_u32 s49, s49, 0
	s_add_u32 s50, s48, 0x100
	s_addc_u32 s51, s49, 0
	s_mul_i32 s60, s58, 2176
	s_mul_hi_u32 s61, s58, 2176
	s_add_u32 s52, s6, s60
	s_addc_u32 s53, s7, s61
	s_add_u32 s52, s52, 0x800
	s_addc_u32 s53, s53, 0
	s_mov_b32 s60, s59
	s_mov_b32 s61, 0
	s_lshl_b64 s[60:61], s[60:61], 12
	s_lshl_b32 s42, s27, 8
	s_add_u32 s54, s10, s60
	s_addc_u32 s55, s11, s61
	s_add_u32 s54, s54, s42
	s_addc_u32 s55, s55, 0
	s_xor_b32 s89, s15, 1
	s_cmp_eq_u32 s15, 1
	s_cselect_b32 s58, s18, 0
	s_add_i32 s88, s14, s58
	s_cmpk_lt_u32 s88, 0x200
	s_cselect_b32 s79, 1, 0
	s_cselect_b32 s88, s88, s14
	s_cselect_b32 s89, s89, s15
	s_cmp_eq_u32 s18, 0x100
	s_cbranch_scc0 .Lad_generic3
	s_and_b32 s42, s88, 0xff
	s_and_b32 s58, s42, 7
	s_lshr_b32 s59, s42, 6
	s_lshl_b32 s59, s59, 3
	s_add_i32 s58, s58, s59
	s_lshr_b32 s59, s88, 8
	s_lshl_b32 s59, s59, 5
	s_add_i32 s58, s58, s59
	s_bfe_u32 s29, s42, 0x30003
	s_branch .Lad_decoded4
.Lad_generic3:
	s_lshr_b32 s58, s88, 3
	s_and_b32 s29, s88, 7
.Lad_decoded4:
	s_lshr_b32 s28, s58, 4
	s_and_b32 s27, s58, 15
	s_sub_i32 s58, 15, s29
	s_cmp_eq_u32 s89, 0
	s_cselect_b32 s16, s29, s58
	s_lshl_b32 s60, s16, 8
	s_lshl_b32 s58, s26, 5
	s_add_i32 s60, s60, s58
	s_lshl_b32 s58, s28, 12
	s_add_i32 s59, s58, s60
	s_mul_i32 s60, s59, 14336
	s_mul_hi_u32 s61, s59, 14336
	s_mul_i32 s42, s27, 384
	s_add_u32 s86, s8, s60
	s_addc_u32 s87, s9, s61
	s_add_u32 s86, s86, s42
	s_addc_u32 s87, s87, 0
	s_mul_i32 s60, s58, 14336
	s_mul_hi_u32 s61, s58, 14336
	s_lshl_b32 s42, s27, 9
	s_add_u32 s80, s8, s60
	s_addc_u32 s81, s9, s61
	s_add_u32 s80, s80, s42
	s_addc_u32 s81, s81, 0
	s_add_u32 s80, s80, 0x1800
	s_addc_u32 s81, s81, 0
	s_add_u32 s82, s80, 0x100
	s_addc_u32 s83, s81, 0
	s_mul_i32 s60, s58, 2176
	s_mul_hi_u32 s61, s58, 2176
	s_add_u32 s84, s6, s60
	s_addc_u32 s85, s7, s61
	s_add_u32 s84, s84, 0x800
	s_addc_u32 s85, s85, 0
	v_add_u32_e32 v229, s43, v226
	v_cvt_f32_u32_e32 v229, v229
	v_mul_f32_e32 v240, 0x3e22f983, v229
	s_barrier
	v_mov_b32_e32 v0, 0
	v_mov_b32_e32 v1, 0
	v_mov_b32_e32 v2, 0
	v_mov_b32_e32 v3, 0
	v_mov_b32_e32 v4, 0
	v_mov_b32_e32 v5, 0
	v_mov_b32_e32 v6, 0
	v_mov_b32_e32 v7, 0
	v_mov_b32_e32 v8, 0
	v_mov_b32_e32 v9, 0
	v_mov_b32_e32 v10, 0
	v_mov_b32_e32 v11, 0
	v_mov_b32_e32 v12, 0
	v_mov_b32_e32 v13, 0
	v_mov_b32_e32 v14, 0
	v_mov_b32_e32 v15, 0
	v_mov_b32_e32 v16, 0
	v_mov_b32_e32 v17, 0
	v_mov_b32_e32 v18, 0
	v_mov_b32_e32 v19, 0
	v_mov_b32_e32 v20, 0
	v_mov_b32_e32 v21, 0
	v_mov_b32_e32 v22, 0
	v_mov_b32_e32 v23, 0
	v_mov_b32_e32 v24, 0
	v_mov_b32_e32 v25, 0
	v_mov_b32_e32 v26, 0
	v_mov_b32_e32 v27, 0
	v_mov_b32_e32 v28, 0
	v_mov_b32_e32 v29, 0
	v_mov_b32_e32 v30, 0
	v_mov_b32_e32 v31, 0
	v_mov_b32_e32 v32, 0
	v_mov_b32_e32 v33, 0
	v_mov_b32_e32 v34, 0
	v_mov_b32_e32 v35, 0
	v_mov_b32_e32 v36, 0
	v_mov_b32_e32 v37, 0
	v_mov_b32_e32 v38, 0
	v_mov_b32_e32 v39, 0
	v_mov_b32_e32 v40, 0
	v_mov_b32_e32 v41, 0
	v_mov_b32_e32 v42, 0
	v_mov_b32_e32 v43, 0
	v_mov_b32_e32 v44, 0
	v_mov_b32_e32 v45, 0
	v_mov_b32_e32 v46, 0
	v_mov_b32_e32 v47, 0
	v_mov_b32_e32 v48, 0
	v_mov_b32_e32 v49, 0
	v_mov_b32_e32 v50, 0
	v_mov_b32_e32 v51, 0
	v_mov_b32_e32 v52, 0
	v_mov_b32_e32 v53, 0
	v_mov_b32_e32 v54, 0
	v_mov_b32_e32 v55, 0
	v_mov_b32_e32 v56, 0
	v_mov_b32_e32 v57, 0
	v_mov_b32_e32 v58, 0
	v_mov_b32_e32 v59, 0
	v_mov_b32_e32 v60, 0
	v_mov_b32_e32 v61, 0
	v_mov_b32_e32 v62, 0
	v_mov_b32_e32 v63, 0
	v_mov_b32_e32 v224, 0
	v_mov_b32_e32 v225, 0
	s_mov_b32 s40, 0
	s_cmp_eq_u32 s77, 0
	s_cbranch_scc1 .Lad_notfirst
	s_mov_b64 s[30:31], s[48:49]
	s_mov_b64 s[36:37], s[52:53]
	s_mov_b64 s[34:35], s[50:51]
	global_load_dwordx4 v[160:163], v219, s[30:31]
	global_load_dwordx4 v[164:167], v220, s[30:31]
	global_load_dwordx4 v[168:171], v221, s[36:37]
	global_load_dwordx4 v[112:115], v237, s[46:47] offset:0
	global_load_dwordx4 v[116:119], v237, s[46:47] offset:32
	global_load_dwordx4 v[120:123], v237, s[46:47] offset:64
	global_load_dwordx4 v[124:127], v237, s[46:47] offset:96
	global_load_dwordx4 v[128:131], v237, s[46:47] offset:128
	global_load_dwordx4 v[132:135], v237, s[46:47] offset:160
	global_load_dwordx4 v[136:139], v237, s[46:47] offset:192
	global_load_dwordx4 v[140:143], v237, s[46:47] offset:224
	global_load_dwordx4 v[144:147], v237, s[46:47] offset:256
	global_load_dwordx4 v[148:151], v237, s[46:47] offset:288
	global_load_dwordx4 v[152:155], v237, s[46:47] offset:320
	global_load_dwordx4 v[156:159], v237, s[46:47] offset:352
	s_add_u32 s30, s30, 0xe0000
	s_addc_u32 s31, s31, 0
	s_add_u32 s36, s36, 0x22000
	s_addc_u32 s37, s37, 0
	s_waitcnt vmcnt(12)
	ds_write_b128 v216, v[160:163] offset:40960
	ds_write_b128 v216, v[164:167] offset:57856
	ds_write_b128 v217, v[168:171] offset:40960
	s_waitcnt lgkmcnt(0)
	global_load_dwordx4 v[160:163], v219, s[30:31]
	global_load_dwordx4 v[164:167], v220, s[30:31]
	global_load_dwordx4 v[168:171], v221, s[36:37]
	global_load_dwordx4 v[172:175], v222, s[34:35]
	global_load_dwordx4 v[176:179], v223, s[34:35]
	s_add_u32 s30, s30, 0xe0000
	s_addc_u32 s31, s31, 0
	s_add_u32 s36, s36, 0x22000
	s_addc_u32 s37, s37, 0
	s_add_u32 s34, s34, 0xe0000
	s_addc_u32 s35, s35, 0
	s_waitcnt vmcnt(5)
	s_branch .Lad_qready

; template <int DQK, int KA8, int DV, bool BIAS, bool JOINT>
; DI void attn_core(LAS unsigned char* lds, const bf16_t* Qrow, const bf16_t* KpA, int ldkA, const bf16_t* KpB, int ldkB, const bf16_t* Vp, int ldv,
;                   int qb, int wid, int lane, const float* qng  , f32x16 (&O)[DV / 32]) {
;     ...
;     bf16x8 qf[DQK / 16];
; #pragma unroll
;     for (int s = 0; s < DQK / 16; ++s) qf[s] = *(const bf16x8*)(Qrow + 16 * s + 8 * hh);
;     if constexpr (DQK == 192) {
;         if (qng) {
;             float ssn = 0.f, ssr = 0.f;
; #pragma unroll
;             for (int s = 0; s < 12; ++s) { float f[8]; unpack8(__builtin_bit_cast(u32x4, qf[s]), f); float t = 0.f;
; #pragma unroll
;                 for (int e = 0; e < 8; ++e) t += f[e] * f[e];
;                 if (s < 8) ssn += t; else ssr += t; }
.Lad_qready:
	v_lshlrev_b32_e32 v229, 16, v112
	v_and_b32_e32 v230, 0xffff0000, v112
	v_mul_f32_e32 v232, v229, v229
	v_fmac_f32_e32 v232, v230, v230
	v_lshlrev_b32_e32 v229, 16, v113
	v_and_b32_e32 v230, 0xffff0000, v113
	v_fmac_f32_e32 v232, v229, v229
	v_fmac_f32_e32 v232, v230, v230
	v_lshlrev_b32_e32 v229, 16, v114
	v_and_b32_e32 v230, 0xffff0000, v114
	v_fmac_f32_e32 v232, v229, v229
	v_fmac_f32_e32 v232, v230, v230
	v_lshlrev_b32_e32 v229, 16, v115
	v_and_b32_e32 v230, 0xffff0000, v115
	v_fmac_f32_e32 v232, v229, v229
	v_fmac_f32_e32 v232, v230, v230
	v_lshlrev_b32_e32 v229, 16, v116
	v_and_b32_e32 v230, 0xffff0000, v116
	v_fmac_f32_e32 v232, v229, v229
	v_fmac_f32_e32 v232, v230, v230
	v_lshlrev_b32_e32 v229, 16, v117
	v_and_b32_e32 v230, 0xffff0000, v117
	v_fmac_f32_e32 v232, v229, v229
	v_fmac_f32_e32 v232, v230, v230
	v_lshlrev_b32_e32 v229, 16, v118
	v_and_b32_e32 v230, 0xffff0000, v118
	v_fmac_f32_e32 v232, v229, v229
	v_fmac_f32_e32 v232, v230, v230
	v_lshlrev_b32_e32 v229, 16, v119
	v_and_b32_e32 v230, 0xffff0000, v119
	v_fmac_f32_e32 v232, v229, v229
	v_fmac_f32_e32 v232, v230, v230
	v_lshlrev_b32_e32 v229, 16, v120
	v_and_b32_e32 v230, 0xffff0000, v120
	v_fmac_f32_e32 v232, v229, v229
	v_fmac_f32_e32 v232, v230, v230
	v_lshlrev_b32_e32 v229, 16, v121
	v_and_b32_e32 v230, 0xffff0000, v121
	v_fmac_f32_e32 v232, v229, v229
	v_fmac_f32_e32 v232, v230, v230
	v_lshlrev_b32_e32 v229, 16, v122
	v_and_b32_e32 v230, 0xffff0000, v122
	v_fmac_f32_e32 v232, v229, v229
	v_fmac_f32_e32 v232, v230, v230
	v_lshlrev_b32_e32 v229, 16, v123
	v_and_b32_e32 v230, 0xffff0000, v123
	v_fmac_f32_e32 v232, v229, v229
	v_fmac_f32_e32 v232, v230, v230
	v_lshlrev_b32_e32 v229, 16, v124
	v_and_b32_e32 v230, 0xffff0000, v124
	v_fmac_f32_e32 v232, v229, v229
	v_fmac_f32_e32 v232, v230, v230
	v_lshlrev_b32_e32 v229, 16, v125
	v_and_b32_e32 v230, 0xffff0000, v125
	v_fmac_f32_e32 v232, v229, v229
	v_fmac_f32_e32 v232, v230, v230
	v_lshlrev_b32_e32 v229, 16, v126
	v_and_b32_e32 v230, 0xffff0000, v126
	v_fmac_f32_e32 v232, v229, v229
	v_fmac_f32_e32 v232, v230, v230
	v_lshlrev_b32_e32 v229, 16, v127
	v_and_b32_e32 v230, 0xffff0000, v127
	v_fmac_f32_e32 v232, v229, v229
	v_fmac_f32_e32 v232, v230, v230
	v_lshlrev_b32_e32 v229, 16, v128
	v_and_b32_e32 v230, 0xffff0000, v128
	v_fmac_f32_e32 v232, v229, v229
	v_fmac_f32_e32 v232, v230, v230
	v_lshlrev_b32_e32 v229, 16, v129
	v_and_b32_e32 v230, 0xffff0000, v129
	v_fmac_f32_e32 v232, v229, v229
	v_fmac_f32_e32 v232, v230, v230
	v_lshlrev_b32_e32 v229, 16, v130
	v_and_b32_e32 v230, 0xffff0000, v130
	v_fmac_f32_e32 v232, v229, v229
	v_fmac_f32_e32 v232, v230, v230
	v_lshlrev_b32_e32 v229, 16, v131
	v_and_b32_e32 v230, 0xffff0000, v131
	v_fmac_f32_e32 v232, v229, v229
	v_fmac_f32_e32 v232, v230, v230
	v_lshlrev_b32_e32 v229, 16, v132
	v_and_b32_e32 v230, 0xffff0000, v132
	v_fmac_f32_e32 v232, v229, v229
	v_fmac_f32_e32 v232, v230, v230
	v_lshlrev_b32_e32 v229, 16, v133
	v_and_b32_e32 v230, 0xffff0000, v133
	v_fmac_f32_e32 v232, v229, v229
	v_fmac_f32_e32 v232, v230, v230
	v_lshlrev_b32_e32 v229, 16, v134
	v_and_b32_e32 v230, 0xffff0000, v134
	v_fmac_f32_e32 v232, v229, v229
	v_fmac_f32_e32 v232, v230, v230
	v_lshlrev_b32_e32 v229, 16, v135
	v_and_b32_e32 v230, 0xffff0000, v135
	v_fmac_f32_e32 v232, v229, v229
	v_fmac_f32_e32 v232, v230, v230
	v_lshlrev_b32_e32 v229, 16, v136
	v_and_b32_e32 v230, 0xffff0000, v136
	v_fmac_f32_e32 v232, v229, v229
	v_fmac_f32_e32 v232, v230, v230
	v_lshlrev_b32_e32 v229, 16, v137
	v_and_b32_e32 v230, 0xffff0000, v137
	v_fmac_f32_e32 v232, v229, v229
	v_fmac_f32_e32 v232, v230, v230
	v_lshlrev_b32_e32 v229, 16, v138
	v_and_b32_e32 v230, 0xffff0000, v138
	v_fmac_f32_e32 v232, v229, v229
	v_fmac_f32_e32 v232, v230, v230
	v_lshlrev_b32_e32 v229, 16, v139
	v_and_b32_e32 v230, 0xffff0000, v139
	v_fmac_f32_e32 v232, v229, v229
	v_fmac_f32_e32 v232, v230, v230
	v_lshlrev_b32_e32 v229, 16, v140
	v_and_b32_e32 v230, 0xffff0000, v140
	v_fmac_f32_e32 v232, v229, v229
	v_fmac_f32_e32 v232, v230, v230
	v_lshlrev_b32_e32 v229, 16, v141
	v_and_b32_e32 v230, 0xffff0000, v141
	v_fmac_f32_e32 v232, v229, v229
	v_fmac_f32_e32 v232, v230, v230
	v_lshlrev_b32_e32 v229, 16, v142
	v_and_b32_e32 v230, 0xffff0000, v142
	v_fmac_f32_e32 v232, v229, v229
	v_fmac_f32_e32 v232, v230, v230
	v_lshlrev_b32_e32 v229, 16, v143
	v_and_b32_e32 v230, 0xffff0000, v143
	v_fmac_f32_e32 v232, v229, v229
	v_fmac_f32_e32 v232, v230, v230
	v_lshlrev_b32_e32 v229, 16, v144
	v_and_b32_e32 v230, 0xffff0000, v144
	v_mul_f32_e32 v233, v229, v229
	v_fmac_f32_e32 v233, v230, v230
	v_lshlrev_b32_e32 v229, 16, v145
	v_and_b32_e32 v230, 0xffff0000, v145
	v_fmac_f32_e32 v233, v229, v229
	v_fmac_f32_e32 v233, v230, v230
	v_lshlrev_b32_e32 v229, 16, v146
	v_and_b32_e32 v230, 0xffff0000, v146
	v_fmac_f32_e32 v233, v229, v229
	v_fmac_f32_e32 v233, v230, v230
	v_lshlrev_b32_e32 v229, 16, v147
	v_and_b32_e32 v230, 0xffff0000, v147
	v_fmac_f32_e32 v233, v229, v229
	v_fmac_f32_e32 v233, v230, v230
	v_lshlrev_b32_e32 v229, 16, v148
	v_and_b32_e32 v230, 0xffff0000, v148
	v_fmac_f32_e32 v233, v229, v229
	v_fmac_f32_e32 v233, v230, v230
	v_lshlrev_b32_e32 v229, 16, v149
	v_and_b32_e32 v230, 0xffff0000, v149
	v_fmac_f32_e32 v233, v229, v229
	v_fmac_f32_e32 v233, v230, v230
	v_lshlrev_b32_e32 v229, 16, v150
	v_and_b32_e32 v230, 0xffff0000, v150
	v_fmac_f32_e32 v233, v229, v229
	v_fmac_f32_e32 v233, v230, v230
	v_lshlrev_b32_e32 v229, 16, v151
	v_and_b32_e32 v230, 0xffff0000, v151
	v_fmac_f32_e32 v233, v229, v229
	v_fmac_f32_e32 v233, v230, v230
	v_lshlrev_b32_e32 v229, 16, v152
	v_and_b32_e32 v230, 0xffff0000, v152
	v_fmac_f32_e32 v233, v229, v229
; DI u32x4 pack8(const float (&f)[8]) { u32x4 w; w.x = pk2(f[0], f[1]); w.y = pk2(f[2], f[3]); w.z = pk2(f[4], f[5]); w.w = pk2(f[6], f[7]); return w; }
; template <int DQK, int KA8, int DV, bool BIAS, bool JOINT>
; DI void attn_core(LAS unsigned char* lds, const bf16_t* Qrow, const bf16_t* KpA, int ldkA, const bf16_t* KpB, int ldkB, const bf16_t* Vp, int ldv,
;                   int qb, int wid, int lane, const float* qng  , f32x16 (&O)[DV / 32]) {
;     ...
;             for (int s = 0; s < 12; ++s) { float f[8]; unpack8(__builtin_bit_cast(u32x4, qf[s]), f); float t = 0.f;
; #pragma unroll
;                 for (int e = 0; e < 8; ++e) t += f[e] * f[e];
;                 if (s < 8) ssn += t; else ssr += t; }
;             ssn += __shfl_xor(ssn, 32); ssr += __shfl_xor(ssr, 32);
;             const float qs = 0.07216878364870322f * LOG2E, scn = rsqrtf(ssn * (1.f / 128.f) + EPS) * qs, scr = rsqrtf(ssr * (1.f / 64.f) + EPS) * qs;
; #pragma unroll
;             for (int s = 0; s < 8; ++s) { float f[8]; unpack8(__builtin_bit_cast(u32x4, qf[s]), f);
;                 const f32x4 g0 = *(const f32x4*)(qng + 16 * s + 8 * hh), g1 = *(const f32x4*)(qng + 16 * s + 8 * hh + 4);
; #pragma unroll
;                 for (int e = 0; e < 4; ++e) { f[e] *= scn * g0[e]; f[4 + e] *= scn * g1[e]; }
;                 qf[s] = __builtin_bit_cast(bf16x8, pack8(f)); }
	v_fmac_f32_e32 v233, v230, v230
	v_lshlrev_b32_e32 v229, 16, v153
	v_and_b32_e32 v230, 0xffff0000, v153
	v_fmac_f32_e32 v233, v229, v229
	v_fmac_f32_e32 v233, v230, v230
	v_lshlrev_b32_e32 v229, 16, v154
	v_and_b32_e32 v230, 0xffff0000, v154
	v_fmac_f32_e32 v233, v229, v229
	v_fmac_f32_e32 v233, v230, v230
	v_lshlrev_b32_e32 v229, 16, v155
	v_and_b32_e32 v230, 0xffff0000, v155
	v_fmac_f32_e32 v233, v229, v229
	v_fmac_f32_e32 v233, v230, v230
	v_lshlrev_b32_e32 v229, 16, v156
	v_and_b32_e32 v230, 0xffff0000, v156
	v_fmac_f32_e32 v233, v229, v229
	v_fmac_f32_e32 v233, v230, v230
	v_lshlrev_b32_e32 v229, 16, v157
	v_and_b32_e32 v230, 0xffff0000, v157
	v_fmac_f32_e32 v233, v229, v229
	v_fmac_f32_e32 v233, v230, v230
	v_lshlrev_b32_e32 v229, 16, v158
	v_and_b32_e32 v230, 0xffff0000, v158
	v_fmac_f32_e32 v233, v229, v229
	v_fmac_f32_e32 v233, v230, v230
	v_lshlrev_b32_e32 v229, 16, v159
	v_and_b32_e32 v230, 0xffff0000, v159
	v_fmac_f32_e32 v233, v229, v229
	v_fmac_f32_e32 v233, v230, v230
	v_mov_b32_e32 v230, v232
	v_mov_b32_e32 v231, v232
	s_nop 1
	v_permlane32_swap_b32_e32 v230, v231
	s_nop 1
	v_add_f32_e32 v232, v230, v231
	v_mov_b32_e32 v230, v233
	v_mov_b32_e32 v231, v233
	s_nop 1
	v_permlane32_swap_b32_e32 v230, v231
	s_nop 1
	v_add_f32_e32 v233, v230, v231
	v_mul_f32_e32 v232, 0x3c000000, v232
	v_mul_f32_e32 v233, 0x3c800000, v233
	v_add_f32_e32 v232, 0x358637bd, v232
	v_add_f32_e32 v233, 0x358637bd, v233
	v_rsq_f32_e32 v232, v232
	v_rsq_f32_e32 v233, v233
	s_nop 1
	v_mul_f32_e32 v241, 0x3dd53b95, v232
	v_mul_f32_e32 v242, 0x3dd53b95, v233
	ds_read_b128 v[182:185], v239 offset:0
	ds_read_b128 v[186:189], v239 offset:16
	s_waitcnt lgkmcnt(0)
	v_lshlrev_b32_e32 v229, 16, v112
	v_and_b32_e32 v230, 0xffff0000, v112
	v_mul_f32_e32 v234, v241, v182
	v_mul_f32_e32 v235, v241, v183
	v_mul_f32_e32 v229, v229, v234
	v_mul_f32_e32 v230, v230, v235
	v_cvt_pk_bf16_f32 v112, v229, v230
	v_lshlrev_b32_e32 v229, 16, v113
	v_and_b32_e32 v230, 0xffff0000, v113
	v_mul_f32_e32 v234, v241, v184
	v_mul_f32_e32 v235, v241, v185
	v_mul_f32_e32 v229, v229, v234
	v_mul_f32_e32 v230, v230, v235
	v_cvt_pk_bf16_f32 v113, v229, v230
	v_lshlrev_b32_e32 v229, 16, v114
	v_and_b32_e32 v230, 0xffff0000, v114
	v_mul_f32_e32 v234, v241, v186
	v_mul_f32_e32 v235, v241, v187
	v_mul_f32_e32 v229, v229, v234
	v_mul_f32_e32 v230, v230, v235
	v_cvt_pk_bf16_f32 v114, v229, v230
	v_lshlrev_b32_e32 v229, 16, v115
	v_and_b32_e32 v230, 0xffff0000, v115
	v_mul_f32_e32 v234, v241, v188
	v_mul_f32_e32 v235, v241, v189
	v_mul_f32_e32 v229, v229, v234
	v_mul_f32_e32 v230, v230, v235
	v_cvt_pk_bf16_f32 v115, v229, v230
	ds_read_b128 v[182:185], v239 offset:64
	ds_read_b128 v[186:189], v239 offset:80
	s_waitcnt lgkmcnt(0)
	v_lshlrev_b32_e32 v229, 16, v116
	v_and_b32_e32 v230, 0xffff0000, v116
	v_mul_f32_e32 v234, v241, v182
	v_mul_f32_e32 v235, v241, v183
	v_mul_f32_e32 v229, v229, v234
	v_mul_f32_e32 v230, v230, v235
	v_cvt_pk_bf16_f32 v116, v229, v230
	v_lshlrev_b32_e32 v229, 16, v117
	v_and_b32_e32 v230, 0xffff0000, v117
	v_mul_f32_e32 v234, v241, v184
	v_mul_f32_e32 v235, v241, v185
	v_mul_f32_e32 v229, v229, v234
	v_mul_f32_e32 v230, v230, v235
	v_cvt_pk_bf16_f32 v117, v229, v230
	v_lshlrev_b32_e32 v229, 16, v118
	v_and_b32_e32 v230, 0xffff0000, v118
	v_mul_f32_e32 v234, v241, v186
	v_mul_f32_e32 v235, v241, v187
	v_mul_f32_e32 v229, v229, v234
	v_mul_f32_e32 v230, v230, v235
	v_cvt_pk_bf16_f32 v118, v229, v230
	v_lshlrev_b32_e32 v229, 16, v119
	v_and_b32_e32 v230, 0xffff0000, v119
	v_mul_f32_e32 v234, v241, v188
	v_mul_f32_e32 v235, v241, v189
	v_mul_f32_e32 v229, v229, v234
	v_mul_f32_e32 v230, v230, v235
	v_cvt_pk_bf16_f32 v119, v229, v230
	ds_read_b128 v[182:185], v239 offset:128
	ds_read_b128 v[186:189], v239 offset:144
	s_waitcnt lgkmcnt(0)
	v_lshlrev_b32_e32 v229, 16, v120
	v_and_b32_e32 v230, 0xffff0000, v120
	v_mul_f32_e32 v234, v241, v182
	v_mul_f32_e32 v235, v241, v183
	v_mul_f32_e32 v229, v229, v234
	v_mul_f32_e32 v230, v230, v235
	v_cvt_pk_bf16_f32 v120, v229, v230
	v_lshlrev_b32_e32 v229, 16, v121
	v_and_b32_e32 v230, 0xffff0000, v121
	v_mul_f32_e32 v234, v241, v184
	v_mul_f32_e32 v235, v241, v185
	v_mul_f32_e32 v229, v229, v234
	v_mul_f32_e32 v230, v230, v235
	v_cvt_pk_bf16_f32 v121, v229, v230
	v_lshlrev_b32_e32 v229, 16, v122
	v_and_b32_e32 v230, 0xffff0000, v122
	v_mul_f32_e32 v234, v241, v186
	v_mul_f32_e32 v235, v241, v187
	v_mul_f32_e32 v229, v229, v234
	v_mul_f32_e32 v230, v230, v235
	v_cvt_pk_bf16_f32 v122, v229, v230
	v_lshlrev_b32_e32 v229, 16, v123
	v_and_b32_e32 v230, 0xffff0000, v123
	v_mul_f32_e32 v234, v241, v188
	v_mul_f32_e32 v235, v241, v189
	v_mul_f32_e32 v229, v229, v234
	v_mul_f32_e32 v230, v230, v235
	v_cvt_pk_bf16_f32 v123, v229, v230
	ds_read_b128 v[182:185], v239 offset:192
	ds_read_b128 v[186:189], v239 offset:208
	s_waitcnt lgkmcnt(0)
	v_lshlrev_b32_e32 v229, 16, v124
	v_and_b32_e32 v230, 0xffff0000, v124
	v_mul_f32_e32 v234, v241, v182
	v_mul_f32_e32 v235, v241, v183
	v_mul_f32_e32 v229, v229, v234
	v_mul_f32_e32 v230, v230, v235
	v_cvt_pk_bf16_f32 v124, v229, v230
	v_lshlrev_b32_e32 v229, 16, v125
	v_and_b32_e32 v230, 0xffff0000, v125
	v_mul_f32_e32 v234, v241, v184
	v_mul_f32_e32 v235, v241, v185
	v_mul_f32_e32 v229, v229, v234
	v_mul_f32_e32 v230, v230, v235
	v_cvt_pk_bf16_f32 v125, v229, v230
	v_lshlrev_b32_e32 v229, 16, v126
	v_and_b32_e32 v230, 0xffff0000, v126
	v_mul_f32_e32 v234, v241, v186
	v_mul_f32_e32 v235, v241, v187
	v_mul_f32_e32 v229, v229, v234
	v_mul_f32_e32 v230, v230, v235
	v_cvt_pk_bf16_f32 v126, v229, v230
	v_lshlrev_b32_e32 v229, 16, v127
	v_and_b32_e32 v230, 0xffff0000, v127
	v_mul_f32_e32 v234, v241, v188
	v_mul_f32_e32 v235, v241, v189
	v_mul_f32_e32 v229, v229, v234
	v_mul_f32_e32 v230, v230, v235
	v_cvt_pk_bf16_f32 v127, v229, v230
	ds_read_b128 v[182:185], v239 offset:256
	ds_read_b128 v[186:189], v239 offset:272
	s_waitcnt lgkmcnt(0)
; DI u32x4 pack8(const float (&f)[8]) { u32x4 w; w.x = pk2(f[0], f[1]); w.y = pk2(f[2], f[3]); w.z = pk2(f[4], f[5]); w.w = pk2(f[6], f[7]); return w; }
; template <int DQK, int KA8, int DV, bool BIAS, bool JOINT>
; DI void attn_core(LAS unsigned char* lds, const bf16_t* Qrow, const bf16_t* KpA, int ldkA, const bf16_t* KpB, int ldkB, const bf16_t* Vp, int ldv,
;                   int qb, int wid, int lane, const float* qng  , f32x16 (&O)[DV / 32]) {
;     ...
;             for (int s = 0; s < 8; ++s) { float f[8]; unpack8(__builtin_bit_cast(u32x4, qf[s]), f);
;                 const f32x4 g0 = *(const f32x4*)(qng + 16 * s + 8 * hh), g1 = *(const f32x4*)(qng + 16 * s + 8 * hh + 4);
; #pragma unroll
;                 for (int e = 0; e < 4; ++e) { f[e] *= scn * g0[e]; f[4 + e] *= scn * g1[e]; }
;                 qf[s] = __builtin_bit_cast(bf16x8, pack8(f)); }
;     ...
;                     const float a1 = f1[e] * scr * qng[128 + i], a2 = f2[e] * scr * qng[160 + i];
	v_lshlrev_b32_e32 v229, 16, v128
	v_and_b32_e32 v230, 0xffff0000, v128
	v_mul_f32_e32 v234, v241, v182
	v_mul_f32_e32 v235, v241, v183
	v_mul_f32_e32 v229, v229, v234
	v_mul_f32_e32 v230, v230, v235
	v_cvt_pk_bf16_f32 v128, v229, v230
	v_lshlrev_b32_e32 v229, 16, v129
	v_and_b32_e32 v230, 0xffff0000, v129
	v_mul_f32_e32 v234, v241, v184
	v_mul_f32_e32 v235, v241, v185
	v_mul_f32_e32 v229, v229, v234
	v_mul_f32_e32 v230, v230, v235
	v_cvt_pk_bf16_f32 v129, v229, v230
	v_lshlrev_b32_e32 v229, 16, v130
	v_and_b32_e32 v230, 0xffff0000, v130
	v_mul_f32_e32 v234, v241, v186
	v_mul_f32_e32 v235, v241, v187
	v_mul_f32_e32 v229, v229, v234
	v_mul_f32_e32 v230, v230, v235
	v_cvt_pk_bf16_f32 v130, v229, v230
	v_lshlrev_b32_e32 v229, 16, v131
	v_and_b32_e32 v230, 0xffff0000, v131
	v_mul_f32_e32 v234, v241, v188
	v_mul_f32_e32 v235, v241, v189
	v_mul_f32_e32 v229, v229, v234
	v_mul_f32_e32 v230, v230, v235
	v_cvt_pk_bf16_f32 v131, v229, v230
	ds_read_b128 v[182:185], v239 offset:320
	ds_read_b128 v[186:189], v239 offset:336
	s_waitcnt lgkmcnt(0)
	v_lshlrev_b32_e32 v229, 16, v132
	v_and_b32_e32 v230, 0xffff0000, v132
	v_mul_f32_e32 v234, v241, v182
	v_mul_f32_e32 v235, v241, v183
	v_mul_f32_e32 v229, v229, v234
	v_mul_f32_e32 v230, v230, v235
	v_cvt_pk_bf16_f32 v132, v229, v230
	v_lshlrev_b32_e32 v229, 16, v133
	v_and_b32_e32 v230, 0xffff0000, v133
	v_mul_f32_e32 v234, v241, v184
	v_mul_f32_e32 v235, v241, v185
	v_mul_f32_e32 v229, v229, v234
	v_mul_f32_e32 v230, v230, v235
	v_cvt_pk_bf16_f32 v133, v229, v230
	v_lshlrev_b32_e32 v229, 16, v134
	v_and_b32_e32 v230, 0xffff0000, v134
	v_mul_f32_e32 v234, v241, v186
	v_mul_f32_e32 v235, v241, v187
	v_mul_f32_e32 v229, v229, v234
	v_mul_f32_e32 v230, v230, v235
	v_cvt_pk_bf16_f32 v134, v229, v230
	v_lshlrev_b32_e32 v229, 16, v135
	v_and_b32_e32 v230, 0xffff0000, v135
	v_mul_f32_e32 v234, v241, v188
	v_mul_f32_e32 v235, v241, v189
	v_mul_f32_e32 v229, v229, v234
	v_mul_f32_e32 v230, v230, v235
	v_cvt_pk_bf16_f32 v135, v229, v230
	ds_read_b128 v[182:185], v239 offset:384
	ds_read_b128 v[186:189], v239 offset:400
	s_waitcnt lgkmcnt(0)
	v_lshlrev_b32_e32 v229, 16, v136
	v_and_b32_e32 v230, 0xffff0000, v136
	v_mul_f32_e32 v234, v241, v182
	v_mul_f32_e32 v235, v241, v183
	v_mul_f32_e32 v229, v229, v234
	v_mul_f32_e32 v230, v230, v235
	v_cvt_pk_bf16_f32 v136, v229, v230
	v_lshlrev_b32_e32 v229, 16, v137
	v_and_b32_e32 v230, 0xffff0000, v137
	v_mul_f32_e32 v234, v241, v184
	v_mul_f32_e32 v235, v241, v185
	v_mul_f32_e32 v229, v229, v234
	v_mul_f32_e32 v230, v230, v235
	v_cvt_pk_bf16_f32 v137, v229, v230
	v_lshlrev_b32_e32 v229, 16, v138
	v_and_b32_e32 v230, 0xffff0000, v138
	v_mul_f32_e32 v234, v241, v186
	v_mul_f32_e32 v235, v241, v187
	v_mul_f32_e32 v229, v229, v234
	v_mul_f32_e32 v230, v230, v235
	v_cvt_pk_bf16_f32 v138, v229, v230
	v_lshlrev_b32_e32 v229, 16, v139
	v_and_b32_e32 v230, 0xffff0000, v139
	v_mul_f32_e32 v234, v241, v188
	v_mul_f32_e32 v235, v241, v189
	v_mul_f32_e32 v229, v229, v234
	v_mul_f32_e32 v230, v230, v235
	v_cvt_pk_bf16_f32 v139, v229, v230
	ds_read_b128 v[182:185], v239 offset:448
	ds_read_b128 v[186:189], v239 offset:464
	s_waitcnt lgkmcnt(0)
	v_lshlrev_b32_e32 v229, 16, v140
	v_and_b32_e32 v230, 0xffff0000, v140
	v_mul_f32_e32 v234, v241, v182
	v_mul_f32_e32 v235, v241, v183
	v_mul_f32_e32 v229, v229, v234
	v_mul_f32_e32 v230, v230, v235
	v_cvt_pk_bf16_f32 v140, v229, v230
	v_lshlrev_b32_e32 v229, 16, v141
	v_and_b32_e32 v230, 0xffff0000, v141
	v_mul_f32_e32 v234, v241, v184
	v_mul_f32_e32 v235, v241, v185
	v_mul_f32_e32 v229, v229, v234
	v_mul_f32_e32 v230, v230, v235
	v_cvt_pk_bf16_f32 v141, v229, v230
	v_lshlrev_b32_e32 v229, 16, v142
	v_and_b32_e32 v230, 0xffff0000, v142
	v_mul_f32_e32 v234, v241, v186
	v_mul_f32_e32 v235, v241, v187
	v_mul_f32_e32 v229, v229, v234
	v_mul_f32_e32 v230, v230, v235
	v_cvt_pk_bf16_f32 v142, v229, v230
	v_lshlrev_b32_e32 v229, 16, v143
	v_and_b32_e32 v230, 0xffff0000, v143
	v_mul_f32_e32 v234, v241, v188
	v_mul_f32_e32 v235, v241, v189
	v_mul_f32_e32 v229, v229, v234
	v_mul_f32_e32 v230, v230, v235
	v_cvt_pk_bf16_f32 v143, v229, v230
	ds_read_b128 v[182:185], v239 offset:512
	ds_read_b128 v[186:189], v239 offset:528
	ds_read_b128 v[190:193], v239 offset:640
	ds_read_b128 v[194:197], v239 offset:656
	s_waitcnt lgkmcnt(0)
; DI u32x4 pack8(const float (&f)[8]) { u32x4 w; w.x = pk2(f[0], f[1]); w.y = pk2(f[2], f[3]); w.z = pk2(f[4], f[5]); w.w = pk2(f[6], f[7]); return w; }
; template <int DQK, int KA8, int DV, bool BIAS, bool JOINT>
; DI void attn_core(LAS unsigned char* lds, const bf16_t* Qrow, const bf16_t* KpA, int ldkA, const bf16_t* KpB, int ldkB, const bf16_t* Vp, int ldv,
;                   int qb, int wid, int lane, const float* qng  , f32x16 (&O)[DV / 32]) {
;     ...
;             const float posr = (float)(qb * 256 + wid * 32 + l32) * 0.15915494309189535f;
; #pragma unroll
;             for (int s = 8; s < 10; ++s) { float f1[8], f2[8]; unpack8(__builtin_bit_cast(u32x4, qf[s]), f1); unpack8(__builtin_bit_cast(u32x4, qf[s + 2]), f2);
; #pragma unroll
;                 for (int e = 0; e < 8; ++e) { const int i = 16 * (s - 8) + 8 * hh + e;
;                     const float a1 = f1[e] * scr * qng[128 + i], a2 = f2[e] * scr * qng[160 + i];
;                     float rev = posr * __builtin_amdgcn_exp2f(-(float)i * 0.41524101186092029f); rev -= floorf(rev);
;                     const float sn = __builtin_amdgcn_sinf(rev), cs = __builtin_amdgcn_cosf(rev);
;                     f1[e] = a1 * cs - a2 * sn; f2[e] = a2 * cs + a1 * sn; }
;                 qf[s] = __builtin_bit_cast(bf16x8, pack8(f1)); qf[s + 2] = __builtin_bit_cast(bf16x8, pack8(f2)); }
	v_lshl_add_u32 v229, v227, 3, 0
	v_cvt_f32_u32_e32 v229, v229
	v_mul_f32_e32 v229, 0xbed49a78, v229
	v_exp_f32_e32 v229, v229
	v_lshlrev_b32_e32 v234, 16, v144
	v_lshlrev_b32_e32 v235, 16, v152
	v_mul_f32_e32 v229, v240, v229
	v_mul_f32_e32 v234, v234, v242
	v_mul_f32_e32 v235, v235, v242
	v_fract_f32_e32 v229, v229
	v_mul_f32_e32 v234, v234, v182
	v_mul_f32_e32 v235, v235, v190
	v_sin_f32_e32 v230, v229
	v_cos_f32_e32 v231, v229
	s_nop 1
	v_mul_f32_e32 v236, v235, v230
	v_mul_f32_e32 v233, v234, v230
	v_fma_f32 v243, v234, v231, -v236
	v_fma_f32 v245, v235, v231, v233
	v_lshl_add_u32 v229, v227, 3, 1
	v_cvt_f32_u32_e32 v229, v229
	v_mul_f32_e32 v229, 0xbed49a78, v229
	v_exp_f32_e32 v229, v229
	v_and_b32_e32 v234, 0xffff0000, v144
	v_and_b32_e32 v235, 0xffff0000, v152
	v_mul_f32_e32 v229, v240, v229
	v_mul_f32_e32 v234, v234, v242
	v_mul_f32_e32 v235, v235, v242
	v_fract_f32_e32 v229, v229
	v_mul_f32_e32 v234, v234, v183
	v_mul_f32_e32 v235, v235, v191
	v_sin_f32_e32 v230, v229
	v_cos_f32_e32 v231, v229
	s_nop 1
	v_mul_f32_e32 v236, v235, v230
	v_mul_f32_e32 v233, v234, v230
	v_fma_f32 v244, v234, v231, -v236
	v_fma_f32 v246, v235, v231, v233
	v_cvt_pk_bf16_f32 v144, v243, v244
	v_cvt_pk_bf16_f32 v152, v245, v246
	v_lshl_add_u32 v229, v227, 3, 2
	v_cvt_f32_u32_e32 v229, v229
	v_mul_f32_e32 v229, 0xbed49a78, v229
	v_exp_f32_e32 v229, v229
	v_lshlrev_b32_e32 v234, 16, v145
	v_lshlrev_b32_e32 v235, 16, v153
	v_mul_f32_e32 v229, v240, v229
	v_mul_f32_e32 v234, v234, v242
	v_mul_f32_e32 v235, v235, v242
	v_fract_f32_e32 v229, v229
	v_mul_f32_e32 v234, v234, v184
	v_mul_f32_e32 v235, v235, v192
	v_sin_f32_e32 v230, v229
	v_cos_f32_e32 v231, v229
	s_nop 1
	v_mul_f32_e32 v236, v235, v230
	v_mul_f32_e32 v233, v234, v230
	v_fma_f32 v243, v234, v231, -v236
	v_fma_f32 v245, v235, v231, v233
	v_lshl_add_u32 v229, v227, 3, 3
	v_cvt_f32_u32_e32 v229, v229
	v_mul_f32_e32 v229, 0xbed49a78, v229
	v_exp_f32_e32 v229, v229
	v_and_b32_e32 v234, 0xffff0000, v145
	v_and_b32_e32 v235, 0xffff0000, v153
	v_mul_f32_e32 v229, v240, v229
	v_mul_f32_e32 v234, v234, v242
	v_mul_f32_e32 v235, v235, v242
	v_fract_f32_e32 v229, v229
	v_mul_f32_e32 v234, v234, v185
	v_mul_f32_e32 v235, v235, v193
	v_sin_f32_e32 v230, v229
	v_cos_f32_e32 v231, v229
	s_nop 1
	v_mul_f32_e32 v236, v235, v230
	v_mul_f32_e32 v233, v234, v230
	v_fma_f32 v244, v234, v231, -v236
	v_fma_f32 v246, v235, v231, v233
	v_cvt_pk_bf16_f32 v145, v243, v244
	v_cvt_pk_bf16_f32 v153, v245, v246
	v_lshl_add_u32 v229, v227, 3, 4
	v_cvt_f32_u32_e32 v229, v229
	v_mul_f32_e32 v229, 0xbed49a78, v229
	v_exp_f32_e32 v229, v229
	v_lshlrev_b32_e32 v234, 16, v146
	v_lshlrev_b32_e32 v235, 16, v154
	v_mul_f32_e32 v229, v240, v229
	v_mul_f32_e32 v234, v234, v242
	v_mul_f32_e32 v235, v235, v242
	v_fract_f32_e32 v229, v229
	v_mul_f32_e32 v234, v234, v186
	v_mul_f32_e32 v235, v235, v194
	v_sin_f32_e32 v230, v229
	v_cos_f32_e32 v231, v229
	s_nop 1
	v_mul_f32_e32 v236, v235, v230
	v_mul_f32_e32 v233, v234, v230
	v_fma_f32 v243, v234, v231, -v236
	v_fma_f32 v245, v235, v231, v233
	v_lshl_add_u32 v229, v227, 3, 5
	v_cvt_f32_u32_e32 v229, v229
	v_mul_f32_e32 v229, 0xbed49a78, v229
	v_exp_f32_e32 v229, v229
	v_and_b32_e32 v234, 0xffff0000, v146
	v_and_b32_e32 v235, 0xffff0000, v154
	v_mul_f32_e32 v229, v240, v229
	v_mul_f32_e32 v234, v234, v242
	v_mul_f32_e32 v235, v235, v242
	v_fract_f32_e32 v229, v229
	v_mul_f32_e32 v234, v234, v187
	v_mul_f32_e32 v235, v235, v195
	v_sin_f32_e32 v230, v229
	v_cos_f32_e32 v231, v229
	s_nop 1
	v_mul_f32_e32 v236, v235, v230
	v_mul_f32_e32 v233, v234, v230
	v_fma_f32 v244, v234, v231, -v236
	v_fma_f32 v246, v235, v231, v233
	v_cvt_pk_bf16_f32 v146, v243, v244
	v_cvt_pk_bf16_f32 v154, v245, v246
	v_lshl_add_u32 v229, v227, 3, 6
	v_cvt_f32_u32_e32 v229, v229
	v_mul_f32_e32 v229, 0xbed49a78, v229
	v_exp_f32_e32 v229, v229
	v_lshlrev_b32_e32 v234, 16, v147
	v_lshlrev_b32_e32 v235, 16, v155
	v_mul_f32_e32 v229, v240, v229
	v_mul_f32_e32 v234, v234, v242
	v_mul_f32_e32 v235, v235, v242
	v_fract_f32_e32 v229, v229
	v_mul_f32_e32 v234, v234, v188
	v_mul_f32_e32 v235, v235, v196
	v_sin_f32_e32 v230, v229
	v_cos_f32_e32 v231, v229
	s_nop 1
	v_mul_f32_e32 v236, v235, v230
	v_mul_f32_e32 v233, v234, v230
	v_fma_f32 v243, v234, v231, -v236
	v_fma_f32 v245, v235, v231, v233
	v_lshl_add_u32 v229, v227, 3, 7
	v_cvt_f32_u32_e32 v229, v229
	v_mul_f32_e32 v229, 0xbed49a78, v229
	v_exp_f32_e32 v229, v229
	v_and_b32_e32 v234, 0xffff0000, v147
	v_and_b32_e32 v235, 0xffff0000, v155
	v_mul_f32_e32 v229, v240, v229
	v_mul_f32_e32 v234, v234, v242
	v_mul_f32_e32 v235, v235, v242
	v_fract_f32_e32 v229, v229
	v_mul_f32_e32 v234, v234, v189
	v_mul_f32_e32 v235, v235, v197
	v_sin_f32_e32 v230, v229
	v_cos_f32_e32 v231, v229
	s_nop 1
	v_mul_f32_e32 v236, v235, v230
	v_mul_f32_e32 v233, v234, v230
	v_fma_f32 v244, v234, v231, -v236
	v_fma_f32 v246, v235, v231, v233
	v_cvt_pk_bf16_f32 v147, v243, v244
	v_cvt_pk_bf16_f32 v155, v245, v246
	ds_read_b128 v[182:185], v239 offset:576
	ds_read_b128 v[186:189], v239 offset:592
	ds_read_b128 v[190:193], v239 offset:704
	ds_read_b128 v[194:197], v239 offset:720
	s_waitcnt lgkmcnt(0)
; DI u32x4 pack8(const float (&f)[8]) { u32x4 w; w.x = pk2(f[0], f[1]); w.y = pk2(f[2], f[3]); w.z = pk2(f[4], f[5]); w.w = pk2(f[6], f[7]); return w; }
; template <int DQK, int KA8, int DV, bool BIAS, bool JOINT>
; DI void attn_core(LAS unsigned char* lds, const bf16_t* Qrow, const bf16_t* KpA, int ldkA, const bf16_t* KpB, int ldkB, const bf16_t* Vp, int ldv,
;                   int qb, int wid, int lane, const float* qng  , f32x16 (&O)[DV / 32]) {
;     ...
;             const float posr = (float)(qb * 256 + wid * 32 + l32) * 0.15915494309189535f;
; #pragma unroll
;             for (int s = 8; s < 10; ++s) { float f1[8], f2[8]; unpack8(__builtin_bit_cast(u32x4, qf[s]), f1); unpack8(__builtin_bit_cast(u32x4, qf[s + 2]), f2);
; #pragma unroll
;                 for (int e = 0; e < 8; ++e) { const int i = 16 * (s - 8) + 8 * hh + e;
;                     const float a1 = f1[e] * scr * qng[128 + i], a2 = f2[e] * scr * qng[160 + i];
;                     float rev = posr * __builtin_amdgcn_exp2f(-(float)i * 0.41524101186092029f); rev -= floorf(rev);
;                     const float sn = __builtin_amdgcn_sinf(rev), cs = __builtin_amdgcn_cosf(rev);
;                     f1[e] = a1 * cs - a2 * sn; f2[e] = a2 * cs + a1 * sn; }
;                 qf[s] = __builtin_bit_cast(bf16x8, pack8(f1)); qf[s + 2] = __builtin_bit_cast(bf16x8, pack8(f2)); }
;             __builtin_amdgcn_sched_barrier(0);
	v_lshl_add_u32 v229, v227, 3, 16
	v_cvt_f32_u32_e32 v229, v229
	v_mul_f32_e32 v229, 0xbed49a78, v229
	v_exp_f32_e32 v229, v229
	v_lshlrev_b32_e32 v234, 16, v148
	v_lshlrev_b32_e32 v235, 16, v156
	v_mul_f32_e32 v229, v240, v229
	v_mul_f32_e32 v234, v234, v242
	v_mul_f32_e32 v235, v235, v242
	v_fract_f32_e32 v229, v229
	v_mul_f32_e32 v234, v234, v182
	v_mul_f32_e32 v235, v235, v190
	v_sin_f32_e32 v230, v229
	v_cos_f32_e32 v231, v229
	s_nop 1
	v_mul_f32_e32 v236, v235, v230
	v_mul_f32_e32 v233, v234, v230
	v_fma_f32 v243, v234, v231, -v236
	v_fma_f32 v245, v235, v231, v233
	v_lshl_add_u32 v229, v227, 3, 17
	v_cvt_f32_u32_e32 v229, v229
	v_mul_f32_e32 v229, 0xbed49a78, v229
	v_exp_f32_e32 v229, v229
	v_and_b32_e32 v234, 0xffff0000, v148
	v_and_b32_e32 v235, 0xffff0000, v156
	v_mul_f32_e32 v229, v240, v229
	v_mul_f32_e32 v234, v234, v242
	v_mul_f32_e32 v235, v235, v242
	v_fract_f32_e32 v229, v229
	v_mul_f32_e32 v234, v234, v183
	v_mul_f32_e32 v235, v235, v191
	v_sin_f32_e32 v230, v229
	v_cos_f32_e32 v231, v229
	s_nop 1
	v_mul_f32_e32 v236, v235, v230
	v_mul_f32_e32 v233, v234, v230
	v_fma_f32 v244, v234, v231, -v236
	v_fma_f32 v246, v235, v231, v233
	v_cvt_pk_bf16_f32 v148, v243, v244
	v_cvt_pk_bf16_f32 v156, v245, v246
	v_lshl_add_u32 v229, v227, 3, 18
	v_cvt_f32_u32_e32 v229, v229
	v_mul_f32_e32 v229, 0xbed49a78, v229
	v_exp_f32_e32 v229, v229
	v_lshlrev_b32_e32 v234, 16, v149
	v_lshlrev_b32_e32 v235, 16, v157
	v_mul_f32_e32 v229, v240, v229
	v_mul_f32_e32 v234, v234, v242
	v_mul_f32_e32 v235, v235, v242
	v_fract_f32_e32 v229, v229
	v_mul_f32_e32 v234, v234, v184
	v_mul_f32_e32 v235, v235, v192
	v_sin_f32_e32 v230, v229
	v_cos_f32_e32 v231, v229
	s_nop 1
	v_mul_f32_e32 v236, v235, v230
	v_mul_f32_e32 v233, v234, v230
	v_fma_f32 v243, v234, v231, -v236
	v_fma_f32 v245, v235, v231, v233
	v_lshl_add_u32 v229, v227, 3, 19
	v_cvt_f32_u32_e32 v229, v229
	v_mul_f32_e32 v229, 0xbed49a78, v229
	v_exp_f32_e32 v229, v229
	v_and_b32_e32 v234, 0xffff0000, v149
	v_and_b32_e32 v235, 0xffff0000, v157
	v_mul_f32_e32 v229, v240, v229
	v_mul_f32_e32 v234, v234, v242
	v_mul_f32_e32 v235, v235, v242
	v_fract_f32_e32 v229, v229
	v_mul_f32_e32 v234, v234, v185
	v_mul_f32_e32 v235, v235, v193
	v_sin_f32_e32 v230, v229
	v_cos_f32_e32 v231, v229
	s_nop 1
	v_mul_f32_e32 v236, v235, v230
	v_mul_f32_e32 v233, v234, v230
	v_fma_f32 v244, v234, v231, -v236
	v_fma_f32 v246, v235, v231, v233
	v_cvt_pk_bf16_f32 v149, v243, v244
	v_cvt_pk_bf16_f32 v157, v245, v246
	v_lshl_add_u32 v229, v227, 3, 20
	v_cvt_f32_u32_e32 v229, v229
	v_mul_f32_e32 v229, 0xbed49a78, v229
	v_exp_f32_e32 v229, v229
	v_lshlrev_b32_e32 v234, 16, v150
	v_lshlrev_b32_e32 v235, 16, v158
	v_mul_f32_e32 v229, v240, v229
	v_mul_f32_e32 v234, v234, v242
	v_mul_f32_e32 v235, v235, v242
	v_fract_f32_e32 v229, v229
	v_mul_f32_e32 v234, v234, v186
	v_mul_f32_e32 v235, v235, v194
	v_sin_f32_e32 v230, v229
	v_cos_f32_e32 v231, v229
	s_nop 1
	v_mul_f32_e32 v236, v235, v230
	v_mul_f32_e32 v233, v234, v230
	v_fma_f32 v243, v234, v231, -v236
	v_fma_f32 v245, v235, v231, v233
	v_lshl_add_u32 v229, v227, 3, 21
	v_cvt_f32_u32_e32 v229, v229
	v_mul_f32_e32 v229, 0xbed49a78, v229
	v_exp_f32_e32 v229, v229
	v_and_b32_e32 v234, 0xffff0000, v150
	v_and_b32_e32 v235, 0xffff0000, v158
	v_mul_f32_e32 v229, v240, v229
	v_mul_f32_e32 v234, v234, v242
	v_mul_f32_e32 v235, v235, v242
	v_fract_f32_e32 v229, v229
	v_mul_f32_e32 v234, v234, v187
	v_mul_f32_e32 v235, v235, v195
	v_sin_f32_e32 v230, v229
	v_cos_f32_e32 v231, v229
	s_nop 1
	v_mul_f32_e32 v236, v235, v230
	v_mul_f32_e32 v233, v234, v230
	v_fma_f32 v244, v234, v231, -v236
	v_fma_f32 v246, v235, v231, v233
	v_cvt_pk_bf16_f32 v150, v243, v244
	v_cvt_pk_bf16_f32 v158, v245, v246
	v_lshl_add_u32 v229, v227, 3, 22
	v_cvt_f32_u32_e32 v229, v229
	v_mul_f32_e32 v229, 0xbed49a78, v229
	v_exp_f32_e32 v229, v229
	v_lshlrev_b32_e32 v234, 16, v151
	v_lshlrev_b32_e32 v235, 16, v159
	v_mul_f32_e32 v229, v240, v229
	v_mul_f32_e32 v234, v234, v242
	v_mul_f32_e32 v235, v235, v242
	v_fract_f32_e32 v229, v229
	v_mul_f32_e32 v234, v234, v188
	v_mul_f32_e32 v235, v235, v196
	v_sin_f32_e32 v230, v229
	v_cos_f32_e32 v231, v229
	s_nop 1
	v_mul_f32_e32 v236, v235, v230
	v_mul_f32_e32 v233, v234, v230
	v_fma_f32 v243, v234, v231, -v236
	v_fma_f32 v245, v235, v231, v233
	v_lshl_add_u32 v229, v227, 3, 23
	v_cvt_f32_u32_e32 v229, v229
	v_mul_f32_e32 v229, 0xbed49a78, v229
	v_exp_f32_e32 v229, v229
	v_and_b32_e32 v234, 0xffff0000, v151
	v_and_b32_e32 v235, 0xffff0000, v159
	v_mul_f32_e32 v229, v240, v229
	v_mul_f32_e32 v234, v234, v242
	v_mul_f32_e32 v235, v235, v242
	v_fract_f32_e32 v229, v229
	v_mul_f32_e32 v234, v234, v189
	v_mul_f32_e32 v235, v235, v197
	v_sin_f32_e32 v230, v229
	v_cos_f32_e32 v231, v229
	s_nop 1
	v_mul_f32_e32 v236, v235, v230
	v_mul_f32_e32 v233, v234, v230
	v_fma_f32 v244, v234, v231, -v236
	v_fma_f32 v246, v235, v231, v233
	v_cvt_pk_bf16_f32 v151, v243, v244
	v_cvt_pk_bf16_f32 v159, v245, v246
	s_barrier
	s_bitcmp0_b32 s26, 2
	s_cbranch_scc1 .Lad_nostag
	s_barrier

; #define LAS __attribute__((address_space(3)))
; template <int DQK, int KA8, int DV, bool BIAS, bool JOINT>
; DI void attn_core(LAS unsigned char* lds, const bf16_t* Qrow, const bf16_t* KpA, int ldkA, const bf16_t* KpB, int ldkB, const bf16_t* Vp, int ldv,
;                   int qb, int wid, int lane, const float* qng  , f32x16 (&O)[DV / 32]) {
;     ...
;     auto gload = [&](int kt) {
; #pragma unroll
;         for (int i = 0; i < NL; ++i) { const int c = tid + i * 512;
;             if (i * 512 < NKC) { const int row = c / KC, cc = c % KC;
;                 const bf16_t* src = (cc < KA8) ? KpA + (size_t)(kt * 64 + row) * ldkA + cc * 8 : KpB + (size_t)(kt * 64 + row) * ldkB + (cc - KA8) * 8;
;                 stg[i] = *(const u32x4*)src; }
;             else { const int c2 = c - NKC, row = c2 / VC, cc = c2 % VC; stg[i] = *(const u32x4*)(Vp + (size_t)(kt * 64 + row) * ldv + cc * 8); } }
;     ...
;     for (int kt = 0; kt < nkt; ++kt) {
;         if (kt + 1 < nkt) gload(kt + 1);
;         if (JOINT && kt <= myc) {
;             LAS unsigned char* kb = lds + (kt & 1) * STG; LAS unsigned char* vb = kb + 64 * KROW;
;             const bool far = (kt * 64 + 63 - q0w <= -91);
;             f32x16 S0, S1;
.Lad_loop:
	s_add_i32 s58, s24, 2
	s_cmp_eq_u32 s58, s17
	s_cselect_b64 s[30:31], s[80:81], s[30:31]
	s_cselect_b64 s[36:37], s[84:85], s[36:37]
	s_add_i32 s58, s25, 1
	s_cmp_eq_u32 s24, 0
	s_cbranch_scc1 .Lad_x0_qk
	s_cmp_gt_u32 s24, s58
	s_cbranch_scc1 .Lad_x0_none
	s_cmp_eq_u32 s24, s58
	s_cbranch_scc1 .Lad_x0_pv
; template <int DQK, int KA8, int DV, bool BIAS, bool JOINT>
; DI void attn_core(LAS unsigned char* lds, const bf16_t* Qrow, const bf16_t* KpA, int ldkA, const bf16_t* KpB, int ldkB, const bf16_t* Vp, int ldv,
;                   int qb, int wid, int lane, const float* qng  , f32x16 (&O)[DV / 32]) {
;     ...
;     for (int kt = 0; kt < nkt; ++kt) {
;         if (kt + 1 < nkt) gload(kt + 1);
;         if (JOINT && kt <= myc) {
;             LAS unsigned char* kb = lds + (kt & 1) * STG; LAS unsigned char* vb = kb + 64 * KROW;
;             const bool far = (kt * 64 + 63 - q0w <= -91);
;             f32x16 S0, S1;
; #pragma unroll
;             for (int i = 0; i < 16; ++i) { S0[i] = 0.f; S1[i] = 0.f; }
; #pragma unroll
;             for (int s = 0; s < DQK / 16; ++s) {
;                 const bf16x8 k0 = *(LAS const bf16x8*)(kb + koff + 32 * s), k1 = *(LAS const bf16x8*)(kb + koff + 32 * KROW + 32 * s);
;                 S0 = mfma32(k0, qf[s], S0); S1 = mfma32(k1, qf[s], S1);
;             }
;             if (BIAS && !far) {
;                 const int rb = kt * 64 - (q0w + l32) + 128;
; #pragma unroll
;                 for (int i = 0; i < 16; ++i) { const int i0 = rb + crow(i, hh); S0[i] += btab[i0 < 0 ? 0 : i0]; S1[i] += btab[i0 + 32 < 0 ? 0 : i0 + 32]; }
;             }
;             if (mnz) {
; #pragma unroll
;                 for (int i = 0; i < 16; ++i) { S0[i] -= m; S1[i] -= m; }
;             }
;             float mx = fmaxf(S0[0], S1[0]);
; #pragma unroll
;             for (int i = 1; i < 16; ++i) mx = fmaxf(mx, fmaxf(S0[i], S1[i]));
;             mx = fmaxf(mx, __shfl_xor(mx, 32));
;             if (__any(mx > 64.f || (kt == 0 && mx < -64.f))) {
;                 const float dm = (mx > 64.f || (kt == 0 && mx < -64.f)) ? mx : 0.f, alpha = __builtin_amdgcn_exp2f(-dm); m += dm; mnz = true;
;                 l *= alpha;
; #pragma unroll
;                 for (int dt = 0; dt < DV / 32; ++dt) O[dt] *= alpha;
; #pragma unroll
;                 for (int i = 0; i < 16; ++i) { S0[i] -= dm; S1[i] -= dm; }
;             }
;             float ps = 0.f;
; #pragma unroll
;             for (int i = 0; i < 16; ++i) { S0[i] = __builtin_amdgcn_exp2f(S0[i]); S1[i] = __builtin_amdgcn_exp2f(S1[i]); ps += S0[i] + S1[i]; }
;             l += ps;
; #pragma unroll
;             for (int half = 0; half < 2; ++half)
; #pragma unroll
;                 for (int s = 0; s < 2; ++s) {
	ds_read_b64_tr_b16 v[182:183], v215 offset:20480
	ds_read_b64_tr_b16 v[184:185], v215 offset:23040
	ds_read_b64_tr_b16 v[186:187], v215 offset:20544
	ds_read_b64_tr_b16 v[188:189], v215 offset:23104
	ds_read_b64_tr_b16 v[190:191], v215 offset:20608
	ds_read_b64_tr_b16 v[192:193], v215 offset:23168
	ds_read_b64_tr_b16 v[194:195], v215 offset:20672
	ds_read_b64_tr_b16 v[196:197], v215 offset:23232
	ds_read_b64_tr_b16 v[198:199], v215 offset:25600
	ds_read_b64_tr_b16 v[200:201], v215 offset:28160
	ds_read_b64_tr_b16 v[202:203], v215 offset:25664
	ds_read_b64_tr_b16 v[204:205], v215 offset:28224
	s_waitcnt lgkmcnt(10)
	v_mfma_f32_32x32x16_bf16 v[0:15], v[182:185], v[96:99], v[0:15]
	ds_read_b64_tr_b16 v[206:207], v215 offset:25728
	ds_read_b64_tr_b16 v[208:209], v215 offset:28288
	s_waitcnt lgkmcnt(10)
	v_mfma_f32_32x32x16_bf16 v[16:31], v[186:189], v[96:99], v[16:31]
	ds_read_b64_tr_b16 v[210:211], v215 offset:25792
	ds_read_b64_tr_b16 v[212:213], v215 offset:28352
	s_waitcnt lgkmcnt(10)
	v_mfma_f32_32x32x16_bf16 v[32:47], v[190:193], v[96:99], v[32:47]
	ds_read_b64_tr_b16 v[182:183], v215 offset:30720
	ds_read_b64_tr_b16 v[184:185], v215 offset:33280
	s_waitcnt lgkmcnt(10)
	v_mfma_f32_32x32x16_bf16 v[48:63], v[194:197], v[96:99], v[48:63]
	s_waitcnt vmcnt(0)
	ds_write_b128 v253, v[160:163] offset:0
	ds_read_b64_tr_b16 v[186:187], v215 offset:30784
	ds_read_b64_tr_b16 v[188:189], v215 offset:33344
	s_waitcnt lgkmcnt(11)
	v_mfma_f32_32x32x16_bf16 v[0:15], v[198:201], v[100:103], v[0:15]
	ds_write_b128 v253, v[164:167] offset:16896
	ds_read_b64_tr_b16 v[190:191], v215 offset:30848
	ds_read_b64_tr_b16 v[192:193], v215 offset:33408
	s_waitcnt lgkmcnt(12)
	v_mfma_f32_32x32x16_bf16 v[16:31], v[202:205], v[100:103], v[16:31]
	ds_write_b128 v254, v[168:171] offset:0
	ds_read_b64_tr_b16 v[194:195], v215 offset:30912
	ds_read_b64_tr_b16 v[196:197], v215 offset:33472
	s_waitcnt lgkmcnt(13)
	v_mfma_f32_32x32x16_bf16 v[32:47], v[206:209], v[100:103], v[32:47]
	ds_write_b128 v218, v[172:175] offset:0
	ds_read_b64_tr_b16 v[198:199], v215 offset:35840
	ds_read_b64_tr_b16 v[200:201], v215 offset:38400
	s_waitcnt lgkmcnt(14)
	v_mfma_f32_32x32x16_bf16 v[48:63], v[210:213], v[100:103], v[48:63]
	ds_write_b128 v218, v[176:179] offset:10240
	ds_read_b64_tr_b16 v[202:203], v215 offset:35904
	ds_read_b64_tr_b16 v[204:205], v215 offset:38464
	s_waitcnt lgkmcnt(15)
	v_mfma_f32_32x32x16_bf16 v[0:15], v[182:185], v[104:107], v[0:15]
	global_load_dwordx4 v[172:175], v222, s[34:35]
	ds_read_b64_tr_b16 v[206:207], v215 offset:35968
	ds_read_b64_tr_b16 v[208:209], v215 offset:38528
	s_waitcnt lgkmcnt(14)
	v_mfma_f32_32x32x16_bf16 v[16:31], v[186:189], v[104:107], v[16:31]
	global_load_dwordx4 v[176:179], v223, s[34:35]
	s_add_u32 s34, s34, 0xe0000
	s_addc_u32 s35, s35, 0
	ds_read_b64_tr_b16 v[210:211], v215 offset:36032
	ds_read_b64_tr_b16 v[212:213], v215 offset:38592
	s_waitcnt lgkmcnt(13)
	v_mfma_f32_32x32x16_bf16 v[32:47], v[190:193], v[104:107], v[32:47]
	global_load_dwordx4 v[160:163], v219, s[30:31]
	ds_read_b128 v[182:185], v214 offset:40960
	s_waitcnt lgkmcnt(11)
	v_mfma_f32_32x32x16_bf16 v[48:63], v[194:197], v[104:107], v[48:63]
	global_load_dwordx4 v[164:167], v220, s[30:31]
	s_add_u32 s30, s30, 0xe0000
	s_addc_u32 s31, s31, 0
	ds_read_b128 v[186:189], v214 offset:57856
	s_waitcnt lgkmcnt(9)
	v_mfma_f32_32x32x16_bf16 v[0:15], v[198:201], v[108:111], v[0:15]
	global_load_dwordx4 v[168:171], v221, s[36:37]
	s_add_u32 s36, s36, 0x22000
	s_addc_u32 s37, s37, 0
	ds_read_b128 v[190:193], v214 offset:40992
	s_waitcnt lgkmcnt(7)
	v_mfma_f32_32x32x16_bf16 v[16:31], v[202:205], v[108:111], v[16:31]
	ds_read_b128 v[194:197], v214 offset:57888
	s_waitcnt lgkmcnt(6)
	v_mfma_f32_32x32x16_bf16 v[32:47], v[206:209], v[108:111], v[32:47]
	ds_read_b128 v[198:201], v214 offset:41024
	s_waitcnt lgkmcnt(5)
	v_mfma_f32_32x32x16_bf16 v[48:63], v[210:213], v[108:111], v[48:63]
	ds_read_b128 v[202:205], v214 offset:57920
	s_waitcnt lgkmcnt(5)
	v_mfma_f32_32x32x16_bf16 v[64:79], v[182:185], v[112:115], 0
	ds_read_b128 v[206:209], v214 offset:41056
	s_waitcnt lgkmcnt(5)
	v_mfma_f32_32x32x16_bf16 v[80:95], v[186:189], v[112:115], 0
	ds_read_b128 v[210:213], v214 offset:57952
	s_waitcnt lgkmcnt(5)
	v_mfma_f32_32x32x16_bf16 v[64:79], v[190:193], v[116:119], v[64:79]
	ds_read_b128 v[182:185], v214 offset:41088
	s_waitcnt lgkmcnt(5)
	v_mfma_f32_32x32x16_bf16 v[80:95], v[194:197], v[116:119], v[80:95]
	ds_read_b128 v[186:189], v214 offset:57984
	s_waitcnt lgkmcnt(5)
	v_mfma_f32_32x32x16_bf16 v[64:79], v[198:201], v[120:123], v[64:79]
	ds_read_b128 v[190:193], v214 offset:41120
	s_waitcnt lgkmcnt(5)
	v_mfma_f32_32x32x16_bf16 v[80:95], v[202:205], v[120:123], v[80:95]
	ds_read_b128 v[194:197], v214 offset:58016
	s_waitcnt lgkmcnt(5)
	v_mfma_f32_32x32x16_bf16 v[64:79], v[206:209], v[124:127], v[64:79]
	ds_read_b128 v[198:201], v214 offset:41152
	s_waitcnt lgkmcnt(5)
	v_mfma_f32_32x32x16_bf16 v[80:95], v[210:213], v[124:127], v[80:95]
	ds_read_b128 v[202:205], v214 offset:58048
	s_waitcnt lgkmcnt(5)
	v_mfma_f32_32x32x16_bf16 v[64:79], v[182:185], v[128:131], v[64:79]
	ds_read_b128 v[206:209], v214 offset:41184
	s_waitcnt lgkmcnt(5)
	v_mfma_f32_32x32x16_bf16 v[80:95], v[186:189], v[128:131], v[80:95]
	ds_read_b128 v[210:213], v214 offset:58080
	s_waitcnt lgkmcnt(5)
	v_mfma_f32_32x32x16_bf16 v[64:79], v[190:193], v[132:135], v[64:79]
	ds_read_b128 v[182:185], v214 offset:41216
	s_waitcnt lgkmcnt(5)
	v_mfma_f32_32x32x16_bf16 v[80:95], v[194:197], v[132:135], v[80:95]
	ds_read_b128 v[186:189], v214 offset:58112
	s_waitcnt lgkmcnt(5)
	v_mfma_f32_32x32x16_bf16 v[64:79], v[198:201], v[136:139], v[64:79]
	ds_read_b128 v[190:193], v214 offset:41248
	s_waitcnt lgkmcnt(5)
	v_mfma_f32_32x32x16_bf16 v[80:95], v[202:205], v[136:139], v[80:95]
	ds_read_b128 v[194:197], v214 offset:58144
	s_waitcnt lgkmcnt(5)
	v_mfma_f32_32x32x16_bf16 v[64:79], v[206:209], v[140:143], v[64:79]
	ds_read_b128 v[198:201], v214 offset:41280
	s_waitcnt lgkmcnt(5)
	v_mfma_f32_32x32x16_bf16 v[80:95], v[210:213], v[140:143], v[80:95]
	ds_read_b128 v[202:205], v214 offset:58176
	s_waitcnt lgkmcnt(5)
	v_mfma_f32_32x32x16_bf16 v[64:79], v[182:185], v[144:147], v[64:79]
	ds_read_b128 v[206:209], v214 offset:41312
	s_waitcnt lgkmcnt(5)
	v_mfma_f32_32x32x16_bf16 v[80:95], v[186:189], v[144:147], v[80:95]
	ds_read_b128 v[210:213], v214 offset:58208
	s_waitcnt lgkmcnt(5)
	v_mfma_f32_32x32x16_bf16 v[64:79], v[190:193], v[148:151], v[64:79]
	s_waitcnt lgkmcnt(4)
	v_mfma_f32_32x32x16_bf16 v[80:95], v[194:197], v[148:151], v[80:95]
	s_waitcnt lgkmcnt(3)
	v_mfma_f32_32x32x16_bf16 v[64:79], v[198:201], v[152:155], v[64:79]
	s_waitcnt lgkmcnt(2)
	v_mfma_f32_32x32x16_bf16 v[80:95], v[202:205], v[152:155], v[80:95]
	s_waitcnt lgkmcnt(1)
	v_mfma_f32_32x32x16_bf16 v[64:79], v[206:209], v[156:159], v[64:79]
	s_waitcnt lgkmcnt(0)
	v_mfma_f32_32x32x16_bf16 v[80:95], v[210:213], v[156:159], v[80:95]
	s_branch .Lad_x0_end

; #define LAS __attribute__((address_space(3)))
; template <int DQK, int KA8, int DV, bool BIAS, bool JOINT>
; DI void attn_core(LAS unsigned char* lds, const bf16_t* Qrow, const bf16_t* KpA, int ldkA, const bf16_t* KpB, int ldkB, const bf16_t* Vp, int ldv,
;                   int qb, int wid, int lane, const float* qng  , f32x16 (&O)[DV / 32]) {
;     ...
;     auto gload = [&](int kt) {
; #pragma unroll
;         for (int i = 0; i < NL; ++i) { const int c = tid + i * 512;
;             if (i * 512 < NKC) { const int row = c / KC, cc = c % KC;
;                 const bf16_t* src = (cc < KA8) ? KpA + (size_t)(kt * 64 + row) * ldkA + cc * 8 : KpB + (size_t)(kt * 64 + row) * ldkB + (cc - KA8) * 8;
;                 stg[i] = *(const u32x4*)src; }
;             else { const int c2 = c - NKC, row = c2 / VC, cc = c2 % VC; stg[i] = *(const u32x4*)(Vp + (size_t)(kt * 64 + row) * ldv + cc * 8); } }
;     ...
;     for (int kt = 0; kt < nkt; ++kt) {
;         if (kt + 1 < nkt) gload(kt + 1);
;         if (JOINT && kt <= myc) {
;             LAS unsigned char* kb = lds + (kt & 1) * STG; LAS unsigned char* vb = kb + 64 * KROW;
;             const bool far = (kt * 64 + 63 - q0w <= -91);
;             f32x16 S0, S1;
.Lad_y0_end:
	s_barrier
	s_add_i32 s59, s24, 1
	s_add_i32 s58, s24, 2
	s_cmp_eq_u32 s58, s17
	s_cselect_b64 s[34:35], s[82:83], s[34:35]
	s_add_i32 s58, s25, 1
	s_cmp_gt_u32 s59, s58
	s_cbranch_scc1 .Lad_x1_none
	s_cmp_eq_u32 s59, s58
	s_cbranch_scc1 .Lad_x1_pv
; template <int DQK, int KA8, int DV, bool BIAS, bool JOINT>
; DI void attn_core(LAS unsigned char* lds, const bf16_t* Qrow, const bf16_t* KpA, int ldkA, const bf16_t* KpB, int ldkB, const bf16_t* Vp, int ldv,
;                   int qb, int wid, int lane, const float* qng  , f32x16 (&O)[DV / 32]) {
;     ...
;     for (int kt = 0; kt < nkt; ++kt) {
;         if (kt + 1 < nkt) gload(kt + 1);
;         if (JOINT && kt <= myc) {
;             LAS unsigned char* kb = lds + (kt & 1) * STG; LAS unsigned char* vb = kb + 64 * KROW;
;             const bool far = (kt * 64 + 63 - q0w <= -91);
;             f32x16 S0, S1;
; #pragma unroll
;             for (int i = 0; i < 16; ++i) { S0[i] = 0.f; S1[i] = 0.f; }
; #pragma unroll
;             for (int s = 0; s < DQK / 16; ++s) {
;                 const bf16x8 k0 = *(LAS const bf16x8*)(kb + koff + 32 * s), k1 = *(LAS const bf16x8*)(kb + koff + 32 * KROW + 32 * s);
;                 S0 = mfma32(k0, qf[s], S0); S1 = mfma32(k1, qf[s], S1);
;             }
;             if (BIAS && !far) {
;                 const int rb = kt * 64 - (q0w + l32) + 128;
; #pragma unroll
;                 for (int i = 0; i < 16; ++i) { const int i0 = rb + crow(i, hh); S0[i] += btab[i0 < 0 ? 0 : i0]; S1[i] += btab[i0 + 32 < 0 ? 0 : i0 + 32]; }
;             }
;             if (mnz) {
; #pragma unroll
;                 for (int i = 0; i < 16; ++i) { S0[i] -= m; S1[i] -= m; }
;             }
;             float mx = fmaxf(S0[0], S1[0]);
; #pragma unroll
;             for (int i = 1; i < 16; ++i) mx = fmaxf(mx, fmaxf(S0[i], S1[i]));
;             mx = fmaxf(mx, __shfl_xor(mx, 32));
;             if (__any(mx > 64.f || (kt == 0 && mx < -64.f))) {
;                 const float dm = (mx > 64.f || (kt == 0 && mx < -64.f)) ? mx : 0.f, alpha = __builtin_amdgcn_exp2f(-dm); m += dm; mnz = true;
;                 l *= alpha;
; #pragma unroll
;                 for (int dt = 0; dt < DV / 32; ++dt) O[dt] *= alpha;
; #pragma unroll
;                 for (int i = 0; i < 16; ++i) { S0[i] -= dm; S1[i] -= dm; }
;             }
;             float ps = 0.f;
; #pragma unroll
;             for (int i = 0; i < 16; ++i) { S0[i] = __builtin_amdgcn_exp2f(S0[i]); S1[i] = __builtin_amdgcn_exp2f(S1[i]); ps += S0[i] + S1[i]; }
;             l += ps;
; #pragma unroll
;             for (int half = 0; half < 2; ++half)
; #pragma unroll
;                 for (int s = 0; s < 2; ++s) {
	ds_read_b64_tr_b16 v[182:183], v215 offset:0
	ds_read_b64_tr_b16 v[184:185], v215 offset:2560
	ds_read_b64_tr_b16 v[186:187], v215 offset:64
	ds_read_b64_tr_b16 v[188:189], v215 offset:2624
	ds_read_b64_tr_b16 v[190:191], v215 offset:128
	ds_read_b64_tr_b16 v[192:193], v215 offset:2688
	ds_read_b64_tr_b16 v[194:195], v215 offset:192
	ds_read_b64_tr_b16 v[196:197], v215 offset:2752
	ds_read_b64_tr_b16 v[198:199], v215 offset:5120
	ds_read_b64_tr_b16 v[200:201], v215 offset:7680
	ds_read_b64_tr_b16 v[202:203], v215 offset:5184
	ds_read_b64_tr_b16 v[204:205], v215 offset:7744
	s_waitcnt lgkmcnt(10)
	v_mfma_f32_32x32x16_bf16 v[0:15], v[182:185], v[96:99], v[0:15]
	ds_read_b64_tr_b16 v[206:207], v215 offset:5248
	ds_read_b64_tr_b16 v[208:209], v215 offset:7808
	s_waitcnt lgkmcnt(10)
	v_mfma_f32_32x32x16_bf16 v[16:31], v[186:189], v[96:99], v[16:31]
	ds_read_b64_tr_b16 v[210:211], v215 offset:5312
	ds_read_b64_tr_b16 v[212:213], v215 offset:7872
	s_waitcnt lgkmcnt(10)
	v_mfma_f32_32x32x16_bf16 v[32:47], v[190:193], v[96:99], v[32:47]
	ds_read_b64_tr_b16 v[182:183], v215 offset:10240
	ds_read_b64_tr_b16 v[184:185], v215 offset:12800
	s_waitcnt lgkmcnt(10)
	v_mfma_f32_32x32x16_bf16 v[48:63], v[194:197], v[96:99], v[48:63]
	s_waitcnt vmcnt(0)
	ds_write_b128 v216, v[160:163] offset:40960
	ds_read_b64_tr_b16 v[186:187], v215 offset:10304
	ds_read_b64_tr_b16 v[188:189], v215 offset:12864
	s_waitcnt lgkmcnt(11)
	v_mfma_f32_32x32x16_bf16 v[0:15], v[198:201], v[100:103], v[0:15]
	ds_write_b128 v216, v[164:167] offset:57856
	ds_read_b64_tr_b16 v[190:191], v215 offset:10368
	ds_read_b64_tr_b16 v[192:193], v215 offset:12928
	s_waitcnt lgkmcnt(12)
	v_mfma_f32_32x32x16_bf16 v[16:31], v[202:205], v[100:103], v[16:31]
	ds_write_b128 v217, v[168:171] offset:40960
	ds_read_b64_tr_b16 v[194:195], v215 offset:10432
	ds_read_b64_tr_b16 v[196:197], v215 offset:12992
	s_waitcnt lgkmcnt(13)
	v_mfma_f32_32x32x16_bf16 v[32:47], v[206:209], v[100:103], v[32:47]
	ds_write_b128 v218, v[172:175] offset:20480
	ds_read_b64_tr_b16 v[198:199], v215 offset:15360
	ds_read_b64_tr_b16 v[200:201], v215 offset:17920
	s_waitcnt lgkmcnt(14)
	v_mfma_f32_32x32x16_bf16 v[48:63], v[210:213], v[100:103], v[48:63]
	ds_write_b128 v218, v[176:179] offset:30720
	ds_read_b64_tr_b16 v[202:203], v215 offset:15424
	ds_read_b64_tr_b16 v[204:205], v215 offset:17984
	s_waitcnt lgkmcnt(15)
	v_mfma_f32_32x32x16_bf16 v[0:15], v[182:185], v[104:107], v[0:15]
	global_load_dwordx4 v[172:175], v222, s[34:35]
	ds_read_b64_tr_b16 v[206:207], v215 offset:15488
	ds_read_b64_tr_b16 v[208:209], v215 offset:18048
	s_waitcnt lgkmcnt(14)
	v_mfma_f32_32x32x16_bf16 v[16:31], v[186:189], v[104:107], v[16:31]
	global_load_dwordx4 v[176:179], v223, s[34:35]
	s_add_u32 s34, s34, 0xe0000
	s_addc_u32 s35, s35, 0
	ds_read_b64_tr_b16 v[210:211], v215 offset:15552
	ds_read_b64_tr_b16 v[212:213], v215 offset:18112
	s_waitcnt lgkmcnt(13)
	v_mfma_f32_32x32x16_bf16 v[32:47], v[190:193], v[104:107], v[32:47]
	global_load_dwordx4 v[160:163], v219, s[30:31]
	ds_read_b128 v[182:185], v252 offset:0
	s_waitcnt lgkmcnt(11)
	v_mfma_f32_32x32x16_bf16 v[48:63], v[194:197], v[104:107], v[48:63]
	global_load_dwordx4 v[164:167], v220, s[30:31]
	s_add_u32 s30, s30, 0xe0000
	s_addc_u32 s31, s31, 0
	ds_read_b128 v[186:189], v252 offset:16896
	s_waitcnt lgkmcnt(9)
	v_mfma_f32_32x32x16_bf16 v[0:15], v[198:201], v[108:111], v[0:15]
	global_load_dwordx4 v[168:171], v221, s[36:37]
	s_add_u32 s36, s36, 0x22000
	s_addc_u32 s37, s37, 0
	ds_read_b128 v[190:193], v252 offset:32
	s_waitcnt lgkmcnt(7)
	v_mfma_f32_32x32x16_bf16 v[16:31], v[202:205], v[108:111], v[16:31]
	ds_read_b128 v[194:197], v252 offset:16928
	s_waitcnt lgkmcnt(6)
	v_mfma_f32_32x32x16_bf16 v[32:47], v[206:209], v[108:111], v[32:47]
	ds_read_b128 v[198:201], v252 offset:64
	s_waitcnt lgkmcnt(5)
	v_mfma_f32_32x32x16_bf16 v[48:63], v[210:213], v[108:111], v[48:63]
	ds_read_b128 v[202:205], v252 offset:16960
	s_waitcnt lgkmcnt(5)
	v_mfma_f32_32x32x16_bf16 v[64:79], v[182:185], v[112:115], 0
	ds_read_b128 v[206:209], v252 offset:96
	s_waitcnt lgkmcnt(5)
	v_mfma_f32_32x32x16_bf16 v[80:95], v[186:189], v[112:115], 0
	ds_read_b128 v[210:213], v252 offset:16992
	s_waitcnt lgkmcnt(5)
	v_mfma_f32_32x32x16_bf16 v[64:79], v[190:193], v[116:119], v[64:79]
	ds_read_b128 v[182:185], v252 offset:128
	s_waitcnt lgkmcnt(5)
	v_mfma_f32_32x32x16_bf16 v[80:95], v[194:197], v[116:119], v[80:95]
	ds_read_b128 v[186:189], v252 offset:17024
	s_waitcnt lgkmcnt(5)
	v_mfma_f32_32x32x16_bf16 v[64:79], v[198:201], v[120:123], v[64:79]
	ds_read_b128 v[190:193], v252 offset:160
	s_waitcnt lgkmcnt(5)
	v_mfma_f32_32x32x16_bf16 v[80:95], v[202:205], v[120:123], v[80:95]
	ds_read_b128 v[194:197], v252 offset:17056
	s_waitcnt lgkmcnt(5)
	v_mfma_f32_32x32x16_bf16 v[64:79], v[206:209], v[124:127], v[64:79]
	ds_read_b128 v[198:201], v252 offset:192
	s_waitcnt lgkmcnt(5)
	v_mfma_f32_32x32x16_bf16 v[80:95], v[210:213], v[124:127], v[80:95]
	ds_read_b128 v[202:205], v252 offset:17088
	s_waitcnt lgkmcnt(5)
	v_mfma_f32_32x32x16_bf16 v[64:79], v[182:185], v[128:131], v[64:79]
	ds_read_b128 v[206:209], v252 offset:224
	s_waitcnt lgkmcnt(5)
	v_mfma_f32_32x32x16_bf16 v[80:95], v[186:189], v[128:131], v[80:95]
	ds_read_b128 v[210:213], v252 offset:17120
	s_waitcnt lgkmcnt(5)
	v_mfma_f32_32x32x16_bf16 v[64:79], v[190:193], v[132:135], v[64:79]
	ds_read_b128 v[182:185], v252 offset:256
	s_waitcnt lgkmcnt(5)
	v_mfma_f32_32x32x16_bf16 v[80:95], v[194:197], v[132:135], v[80:95]
	ds_read_b128 v[186:189], v252 offset:17152
	s_waitcnt lgkmcnt(5)
	v_mfma_f32_32x32x16_bf16 v[64:79], v[198:201], v[136:139], v[64:79]
	ds_read_b128 v[190:193], v252 offset:288
	s_waitcnt lgkmcnt(5)
	v_mfma_f32_32x32x16_bf16 v[80:95], v[202:205], v[136:139], v[80:95]
	ds_read_b128 v[194:197], v252 offset:17184
	s_waitcnt lgkmcnt(5)
	v_mfma_f32_32x32x16_bf16 v[64:79], v[206:209], v[140:143], v[64:79]
	ds_read_b128 v[198:201], v252 offset:320
	s_waitcnt lgkmcnt(5)
	v_mfma_f32_32x32x16_bf16 v[80:95], v[210:213], v[140:143], v[80:95]
	ds_read_b128 v[202:205], v252 offset:17216
	s_waitcnt lgkmcnt(5)
	v_mfma_f32_32x32x16_bf16 v[64:79], v[182:185], v[144:147], v[64:79]
	ds_read_b128 v[206:209], v252 offset:352
	s_waitcnt lgkmcnt(5)
	v_mfma_f32_32x32x16_bf16 v[80:95], v[186:189], v[144:147], v[80:95]
	ds_read_b128 v[210:213], v252 offset:17248
	s_waitcnt lgkmcnt(5)
	v_mfma_f32_32x32x16_bf16 v[64:79], v[190:193], v[148:151], v[64:79]
	s_waitcnt lgkmcnt(4)
	v_mfma_f32_32x32x16_bf16 v[80:95], v[194:197], v[148:151], v[80:95]
	s_waitcnt lgkmcnt(3)
	v_mfma_f32_32x32x16_bf16 v[64:79], v[198:201], v[152:155], v[64:79]
	s_waitcnt lgkmcnt(2)
	v_mfma_f32_32x32x16_bf16 v[80:95], v[202:205], v[152:155], v[80:95]
	s_waitcnt lgkmcnt(1)
	v_mfma_f32_32x32x16_bf16 v[64:79], v[206:209], v[156:159], v[64:79]
	s_waitcnt lgkmcnt(0)
	v_mfma_f32_32x32x16_bf16 v[80:95], v[210:213], v[156:159], v[80:95]
	s_branch .Lad_x1_end

; #define LAS __attribute__((address_space(3)))
; DI unsigned pk2(float a, float b) { f32x2 v = {a, b}; bf16v2_t r = __builtin_convertvector(v, bf16v2_t); return __builtin_bit_cast(unsigned, r); }
; DI f32x16 mfma32(bf16x8 a, bf16x8 b, f32x16 c) { return __builtin_amdgcn_mfma_f32_32x32x16_bf16(a, b, c, 0, 0, 0); }
; DI s16x4 trread(LAS unsigned char* p) { return __builtin_amdgcn_ds_read_tr16_b64_v4i16((LAS s16x4*)p); }
; DI bf16x8 cat4(s16x4 lo, s16x4 hi) { return __builtin_shufflevector(lo, hi, 0, 1, 2, 3, 4, 5, 6, 7); }
; template <int DQK, int KA8, int DV, bool BIAS, bool JOINT>
; DI void attn_core(LAS unsigned char* lds, const bf16_t* Qrow, const bf16_t* KpA, int ldkA, const bf16_t* KpB, int ldkB, const bf16_t* Vp, int ldv,
;                   int qb, int wid, int lane, const float* qng  , f32x16 (&O)[DV / 32]) {
;     ...
;     bf16x8 qf[DQK / 16];
; #pragma unroll
;     for (int s = 0; s < DQK / 16; ++s) qf[s] = *(const bf16x8*)(Qrow + 16 * s + 8 * hh);
;     ...
; #pragma unroll
;             for (int half = 0; half < 2; ++half)
; #pragma unroll
;                 for (int s = 0; s < 2; ++s) {
;                     const f32x16& S = half ? S1 : S0;
;                     u32x4 pw; pw.x = pk2(S[8 * s], S[8 * s + 1]); pw.y = pk2(S[8 * s + 2], S[8 * s + 3]); pw.z = pk2(S[8 * s + 4], S[8 * s + 5]); pw.w = pk2(S[8 * s + 6], S[8 * s + 7]);
;                     const bf16x8 pf = __builtin_bit_cast(bf16x8, pw);
;                     LAS unsigned char* vr = vb + vtr + (32 * half + 16 * s) * VROW;
; #pragma unroll
;                     for (int dt = 0; dt < DV / 32; ++dt) {
;                         const bf16x8 vf = cat4(trread(vr + 64 * dt), trread(vr + 8 * VROW + 64 * dt));
;                         O[dt] = mfma32(vf, pf, O[dt]);
;                     }
.Lad_y1_end:
	s_barrier
	s_add_i32 s24, s24, 2
	s_cmp_lt_u32 s24, s17
	s_cbranch_scc1 .Lad_loop
	s_cmp_eq_u32 s79, 0
	s_cbranch_scc1 .Lad_noqpf
	global_load_dwordx4 v[112:115], v237, s[86:87] offset:0
	global_load_dwordx4 v[116:119], v237, s[86:87] offset:32
	global_load_dwordx4 v[120:123], v237, s[86:87] offset:64
	global_load_dwordx4 v[124:127], v237, s[86:87] offset:96
	global_load_dwordx4 v[128:131], v237, s[86:87] offset:128
	global_load_dwordx4 v[132:135], v237, s[86:87] offset:160
	global_load_dwordx4 v[136:139], v237, s[86:87] offset:192
	global_load_dwordx4 v[140:143], v237, s[86:87] offset:224
	global_load_dwordx4 v[144:147], v237, s[86:87] offset:256
	global_load_dwordx4 v[148:151], v237, s[86:87] offset:288
	global_load_dwordx4 v[152:155], v237, s[86:87] offset:320
	global_load_dwordx4 v[156:159], v237, s[86:87] offset:352
.Lad_noqpf:
	s_add_i32 s58, s25, 1
	s_cmp_ge_u32 s58, s17
	s_cbranch_scc0 .Lad_nofpv
	ds_read_b64_tr_b16 v[182:183], v215 offset:20480
	ds_read_b64_tr_b16 v[184:185], v215 offset:23040
	ds_read_b64_tr_b16 v[186:187], v215 offset:20544
	ds_read_b64_tr_b16 v[188:189], v215 offset:23104
	ds_read_b64_tr_b16 v[190:191], v215 offset:20608
	ds_read_b64_tr_b16 v[192:193], v215 offset:23168
	ds_read_b64_tr_b16 v[194:195], v215 offset:20672
	ds_read_b64_tr_b16 v[196:197], v215 offset:23232
	ds_read_b64_tr_b16 v[198:199], v215 offset:25600
	ds_read_b64_tr_b16 v[200:201], v215 offset:28160
	ds_read_b64_tr_b16 v[202:203], v215 offset:25664
	ds_read_b64_tr_b16 v[204:205], v215 offset:28224
	s_waitcnt lgkmcnt(10)
	v_mfma_f32_32x32x16_bf16 v[0:15], v[182:185], v[96:99], v[0:15]
	ds_read_b64_tr_b16 v[206:207], v215 offset:25728
	ds_read_b64_tr_b16 v[208:209], v215 offset:28288
	s_waitcnt lgkmcnt(10)
	v_mfma_f32_32x32x16_bf16 v[16:31], v[186:189], v[96:99], v[16:31]
	ds_read_b64_tr_b16 v[210:211], v215 offset:25792
	ds_read_b64_tr_b16 v[212:213], v215 offset:28352
	s_waitcnt lgkmcnt(10)
	v_mfma_f32_32x32x16_bf16 v[32:47], v[190:193], v[96:99], v[32:47]
	ds_read_b64_tr_b16 v[182:183], v215 offset:30720
	ds_read_b64_tr_b16 v[184:185], v215 offset:33280
	s_waitcnt lgkmcnt(10)
	v_mfma_f32_32x32x16_bf16 v[48:63], v[194:197], v[96:99], v[48:63]
	ds_read_b64_tr_b16 v[186:187], v215 offset:30784
	ds_read_b64_tr_b16 v[188:189], v215 offset:33344
	s_waitcnt lgkmcnt(10)
	v_mfma_f32_32x32x16_bf16 v[0:15], v[198:201], v[100:103], v[0:15]
	ds_read_b64_tr_b16 v[190:191], v215 offset:30848
	ds_read_b64_tr_b16 v[192:193], v215 offset:33408
	s_waitcnt lgkmcnt(10)
	v_mfma_f32_32x32x16_bf16 v[16:31], v[202:205], v[100:103], v[16:31]
	ds_read_b64_tr_b16 v[194:195], v215 offset:30912
	ds_read_b64_tr_b16 v[196:197], v215 offset:33472
	s_waitcnt lgkmcnt(10)
	v_mfma_f32_32x32x16_bf16 v[32:47], v[206:209], v[100:103], v[32:47]
	ds_read_b64_tr_b16 v[198:199], v215 offset:35840
	ds_read_b64_tr_b16 v[200:201], v215 offset:38400
	s_waitcnt lgkmcnt(10)
	v_mfma_f32_32x32x16_bf16 v[48:63], v[210:213], v[100:103], v[48:63]
	ds_read_b64_tr_b16 v[202:203], v215 offset:35904
	ds_read_b64_tr_b16 v[204:205], v215 offset:38464
	s_waitcnt lgkmcnt(10)
	v_mfma_f32_32x32x16_bf16 v[0:15], v[182:185], v[104:107], v[0:15]
	ds_read_b64_tr_b16 v[206:207], v215 offset:35968
	ds_read_b64_tr_b16 v[208:209], v215 offset:38528
	s_waitcnt lgkmcnt(10)
	v_mfma_f32_32x32x16_bf16 v[16:31], v[186:189], v[104:107], v[16:31]
	ds_read_b64_tr_b16 v[210:211], v215 offset:36032
	ds_read_b64_tr_b16 v[212:213], v215 offset:38592
	s_waitcnt lgkmcnt(10)
	v_mfma_f32_32x32x16_bf16 v[32:47], v[190:193], v[104:107], v[32:47]
	s_waitcnt lgkmcnt(8)
	v_mfma_f32_32x32x16_bf16 v[48:63], v[194:197], v[104:107], v[48:63]
	s_waitcnt lgkmcnt(6)
	v_mfma_f32_32x32x16_bf16 v[0:15], v[198:201], v[108:111], v[0:15]
	s_waitcnt lgkmcnt(4)
	v_mfma_f32_32x32x16_bf16 v[16:31], v[202:205], v[108:111], v[16:31]
	s_waitcnt lgkmcnt(2)
	v_mfma_f32_32x32x16_bf16 v[32:47], v[206:209], v[108:111], v[32:47]
	s_waitcnt lgkmcnt(0)
	v_mfma_f32_32x32x16_bf16 v[48:63], v[210:213], v[108:111], v[48:63]

; DI int otid() { int t = threadIdx.x; asm volatile("" : "+v"(t)); return t; }
; DI unsigned pk2(float a, float b) { f32x2 v = {a, b}; bf16v2_t r = __builtin_convertvector(v, bf16v2_t); return __builtin_bit_cast(unsigned, r); }
; DI float silu(float x) { return x / (1.f + __expf(-x)); }
; template <int DQK, int KA8, int DV, bool BIAS, bool JOINT>
; DI void attn_core(LAS unsigned char* lds, const bf16_t* Qrow, const bf16_t* KpA, int ldkA, const bf16_t* KpB, int ldkB, const bf16_t* Vp, int ldv,
;                   int qb, int wid, int lane, const float* qng  , f32x16 (&O)[DV / 32]) {
;     ...
;     l += __shfl_xor(l, 32);
;     const float il = 1.f / l;
; #pragma unroll
;     for (int dt = 0; dt < DV / 32; ++dt) O[dt] *= il;
; DI void phase_attn_d(const Params& p, LAS unsigned char* lds) {
;     ...
;             const int tid2 = otid(), wid2 = tid2 >> 6, lane2 = tid2 & 63;
;             const size_t tokq2 = (size_t)b * SEQ + qb * 256 + wid2 * 32 + (lane2 & 31); const int hh2 = lane2 >> 5;
; #pragma unroll
;             for (int dt = 0; dt < 4; ++dt)
; #pragma unroll
;                 for (int g4 = 0; g4 < 4; ++g4) { const int dv = 32 * dt + 8 * g4 + 4 * hh2;
;                     const u32x2 gw = *(const u32x2*)(gb + tokq2 * DM + h * 128 + dv);
;                     const float g0 = __uint_as_float(gw.x << 16), g1 = __uint_as_float(gw.x & 0xffff0000u), g2 = __uint_as_float(gw.y << 16), g3 = __uint_as_float(gw.y & 0xffff0000u);
;                     u32x2 w; w.x = pk2(O[dt][4 * g4] * silu(g0), O[dt][4 * g4 + 1] * silu(g1)); w.y = pk2(O[dt][4 * g4 + 2] * silu(g2), O[dt][4 * g4 + 3] * silu(g3));
;                     *(u32x2*)(y + tokq2 * DM + h * 128 + dv) = w; }
.Lad_noea:
	global_load_dwordx2 v[182:183], v238, s[54:55] offset:0
	global_load_dwordx2 v[184:185], v238, s[54:55] offset:16
	global_load_dwordx2 v[186:187], v238, s[54:55] offset:32
	global_load_dwordx2 v[188:189], v238, s[54:55] offset:48
	global_load_dwordx2 v[190:191], v238, s[54:55] offset:64
	global_load_dwordx2 v[192:193], v238, s[54:55] offset:80
	global_load_dwordx2 v[194:195], v238, s[54:55] offset:96
	global_load_dwordx2 v[196:197], v238, s[54:55] offset:112
	global_load_dwordx2 v[198:199], v238, s[54:55] offset:128
	global_load_dwordx2 v[200:201], v238, s[54:55] offset:144
	global_load_dwordx2 v[202:203], v238, s[54:55] offset:160
	global_load_dwordx2 v[204:205], v238, s[54:55] offset:176
	global_load_dwordx2 v[206:207], v238, s[54:55] offset:192
	global_load_dwordx2 v[208:209], v238, s[54:55] offset:208
	global_load_dwordx2 v[210:211], v238, s[54:55] offset:224
	global_load_dwordx2 v[212:213], v238, s[54:55] offset:240
	s_nop 15
	v_mov_b32_e32 v230, v225
	v_mov_b32_e32 v231, v225
	s_nop 1
	v_permlane32_swap_b32_e32 v230, v231
	s_nop 1
	v_add_f32_e32 v225, v230, v231
	v_rcp_f32_e32 v229, v225
	s_nop 1
	v_mul_f32_e32 v0, v0, v229
	v_mul_f32_e32 v1, v1, v229
	v_mul_f32_e32 v2, v2, v229
	v_mul_f32_e32 v3, v3, v229
	v_mul_f32_e32 v4, v4, v229
	v_mul_f32_e32 v5, v5, v229
	v_mul_f32_e32 v6, v6, v229
	v_mul_f32_e32 v7, v7, v229
	v_mul_f32_e32 v8, v8, v229
	v_mul_f32_e32 v9, v9, v229
	v_mul_f32_e32 v10, v10, v229
	v_mul_f32_e32 v11, v11, v229
	v_mul_f32_e32 v12, v12, v229
	v_mul_f32_e32 v13, v13, v229
	v_mul_f32_e32 v14, v14, v229
	v_mul_f32_e32 v15, v15, v229
	v_mul_f32_e32 v16, v16, v229
	v_mul_f32_e32 v17, v17, v229
	v_mul_f32_e32 v18, v18, v229
	v_mul_f32_e32 v19, v19, v229
	v_mul_f32_e32 v20, v20, v229
	v_mul_f32_e32 v21, v21, v229
	v_mul_f32_e32 v22, v22, v229
	v_mul_f32_e32 v23, v23, v229
	v_mul_f32_e32 v24, v24, v229
	v_mul_f32_e32 v25, v25, v229
	v_mul_f32_e32 v26, v26, v229
	v_mul_f32_e32 v27, v27, v229
	v_mul_f32_e32 v28, v28, v229
	v_mul_f32_e32 v29, v29, v229
	v_mul_f32_e32 v30, v30, v229
	v_mul_f32_e32 v31, v31, v229
	v_mul_f32_e32 v32, v32, v229
	v_mul_f32_e32 v33, v33, v229
	v_mul_f32_e32 v34, v34, v229
	v_mul_f32_e32 v35, v35, v229
	v_mul_f32_e32 v36, v36, v229
	v_mul_f32_e32 v37, v37, v229
	v_mul_f32_e32 v38, v38, v229
	v_mul_f32_e32 v39, v39, v229
	v_mul_f32_e32 v40, v40, v229
	v_mul_f32_e32 v41, v41, v229
	v_mul_f32_e32 v42, v42, v229
	v_mul_f32_e32 v43, v43, v229
	v_mul_f32_e32 v44, v44, v229
	v_mul_f32_e32 v45, v45, v229
	v_mul_f32_e32 v46, v46, v229
	v_mul_f32_e32 v47, v47, v229
	v_mul_f32_e32 v48, v48, v229
	v_mul_f32_e32 v49, v49, v229
	v_mul_f32_e32 v50, v50, v229
	v_mul_f32_e32 v51, v51, v229
	v_mul_f32_e32 v52, v52, v229
	v_mul_f32_e32 v53, v53, v229
	v_mul_f32_e32 v54, v54, v229
	v_mul_f32_e32 v55, v55, v229
	v_mul_f32_e32 v56, v56, v229
	v_mul_f32_e32 v57, v57, v229
	v_mul_f32_e32 v58, v58, v229
	v_mul_f32_e32 v59, v59, v229
	v_mul_f32_e32 v60, v60, v229
	v_mul_f32_e32 v61, v61, v229
	v_mul_f32_e32 v62, v62, v229
	v_mul_f32_e32 v63, v63, v229
	s_waitcnt vmcnt(0)
	v_lshlrev_b32_e32 v243, 16, v182
	v_and_b32_e32 v244, 0xffff0000, v182
	v_lshlrev_b32_e32 v245, 16, v183
	v_and_b32_e32 v246, 0xffff0000, v183
	v_mul_f32_e32 v247, 0xbfb8aa3b, v243
	v_mul_f32_e32 v248, 0xbfb8aa3b, v244
	v_mul_f32_e32 v249, 0xbfb8aa3b, v245
	v_mul_f32_e32 v250, 0xbfb8aa3b, v246
	v_exp_f32_e32 v247, v247
	v_exp_f32_e32 v248, v248
	v_exp_f32_e32 v249, v249
	v_exp_f32_e32 v250, v250
	s_nop 0
	v_add_f32_e32 v247, 1.0, v247
	v_add_f32_e32 v248, 1.0, v248
	v_add_f32_e32 v249, 1.0, v249
	v_add_f32_e32 v250, 1.0, v250
	v_rcp_f32_e32 v247, v247
	v_rcp_f32_e32 v248, v248
	v_rcp_f32_e32 v249, v249
	v_rcp_f32_e32 v250, v250
	s_nop 0
	v_mul_f32_e32 v243, v243, v247
	v_mul_f32_e32 v244, v244, v248
	v_mul_f32_e32 v245, v245, v249
	v_mul_f32_e32 v246, v246, v250
	v_mul_f32_e32 v0, v0, v243
	v_mul_f32_e32 v1, v1, v244
	v_mul_f32_e32 v2, v2, v245
	v_mul_f32_e32 v3, v3, v246
	v_cvt_pk_bf16_f32 v182, v0, v1
	v_cvt_pk_bf16_f32 v183, v2, v3
	global_store_dwordx2 v238, v[182:183], s[54:55] offset:0
	v_lshlrev_b32_e32 v243, 16, v184
	v_and_b32_e32 v244, 0xffff0000, v184
	v_lshlrev_b32_e32 v245, 16, v185
	v_and_b32_e32 v246, 0xffff0000, v185
	v_mul_f32_e32 v247, 0xbfb8aa3b, v243
	v_mul_f32_e32 v248, 0xbfb8aa3b, v244
	v_mul_f32_e32 v249, 0xbfb8aa3b, v245
	v_mul_f32_e32 v250, 0xbfb8aa3b, v246
	v_exp_f32_e32 v247, v247
	v_exp_f32_e32 v248, v248
	v_exp_f32_e32 v249, v249
	v_exp_f32_e32 v250, v250
	s_nop 0
	v_add_f32_e32 v247, 1.0, v247
	v_add_f32_e32 v248, 1.0, v248
	v_add_f32_e32 v249, 1.0, v249
	v_add_f32_e32 v250, 1.0, v250
	v_rcp_f32_e32 v247, v247
	v_rcp_f32_e32 v248, v248
	v_rcp_f32_e32 v249, v249
	v_rcp_f32_e32 v250, v250
	s_nop 0
	v_mul_f32_e32 v243, v243, v247
	v_mul_f32_e32 v244, v244, v248
	v_mul_f32_e32 v245, v245, v249
	v_mul_f32_e32 v246, v246, v250
	v_mul_f32_e32 v4, v4, v243
	v_mul_f32_e32 v5, v5, v244
	v_mul_f32_e32 v6, v6, v245
	v_mul_f32_e32 v7, v7, v246
	v_cvt_pk_bf16_f32 v184, v4, v5
	v_cvt_pk_bf16_f32 v185, v6, v7
	global_store_dwordx2 v238, v[184:185], s[54:55] offset:16
	v_lshlrev_b32_e32 v243, 16, v186
	v_and_b32_e32 v244, 0xffff0000, v186
	v_lshlrev_b32_e32 v245, 16, v187
	v_and_b32_e32 v246, 0xffff0000, v187
	v_mul_f32_e32 v247, 0xbfb8aa3b, v243
	v_mul_f32_e32 v248, 0xbfb8aa3b, v244
	v_mul_f32_e32 v249, 0xbfb8aa3b, v245
	v_mul_f32_e32 v250, 0xbfb8aa3b, v246
	v_exp_f32_e32 v247, v247
	v_exp_f32_e32 v248, v248
	v_exp_f32_e32 v249, v249
	v_exp_f32_e32 v250, v250
	s_nop 0
	v_add_f32_e32 v247, 1.0, v247
	v_add_f32_e32 v248, 1.0, v248
	v_add_f32_e32 v249, 1.0, v249
	v_add_f32_e32 v250, 1.0, v250
	v_rcp_f32_e32 v247, v247
; DI unsigned pk2(float a, float b) { f32x2 v = {a, b}; bf16v2_t r = __builtin_convertvector(v, bf16v2_t); return __builtin_bit_cast(unsigned, r); }
; DI float silu(float x) { return x / (1.f + __expf(-x)); }
; DI void phase_attn_d(const Params& p, LAS unsigned char* lds) {
;     ...
; #pragma unroll
;             for (int dt = 0; dt < 4; ++dt)
; #pragma unroll
;                 for (int g4 = 0; g4 < 4; ++g4) { const int dv = 32 * dt + 8 * g4 + 4 * hh2;
;                     const u32x2 gw = *(const u32x2*)(gb + tokq2 * DM + h * 128 + dv);
;                     const float g0 = __uint_as_float(gw.x << 16), g1 = __uint_as_float(gw.x & 0xffff0000u), g2 = __uint_as_float(gw.y << 16), g3 = __uint_as_float(gw.y & 0xffff0000u);
;                     u32x2 w; w.x = pk2(O[dt][4 * g4] * silu(g0), O[dt][4 * g4 + 1] * silu(g1)); w.y = pk2(O[dt][4 * g4 + 2] * silu(g2), O[dt][4 * g4 + 3] * silu(g3));
;                     *(u32x2*)(y + tokq2 * DM + h * 128 + dv) = w; }
	v_rcp_f32_e32 v248, v248
	v_rcp_f32_e32 v249, v249
	v_rcp_f32_e32 v250, v250
	s_nop 0
	v_mul_f32_e32 v243, v243, v247
	v_mul_f32_e32 v244, v244, v248
	v_mul_f32_e32 v245, v245, v249
	v_mul_f32_e32 v246, v246, v250
	v_mul_f32_e32 v8, v8, v243
	v_mul_f32_e32 v9, v9, v244
	v_mul_f32_e32 v10, v10, v245
	v_mul_f32_e32 v11, v11, v246
	v_cvt_pk_bf16_f32 v186, v8, v9
	v_cvt_pk_bf16_f32 v187, v10, v11
	global_store_dwordx2 v238, v[186:187], s[54:55] offset:32
	v_lshlrev_b32_e32 v243, 16, v188
	v_and_b32_e32 v244, 0xffff0000, v188
	v_lshlrev_b32_e32 v245, 16, v189
	v_and_b32_e32 v246, 0xffff0000, v189
	v_mul_f32_e32 v247, 0xbfb8aa3b, v243
	v_mul_f32_e32 v248, 0xbfb8aa3b, v244
	v_mul_f32_e32 v249, 0xbfb8aa3b, v245
	v_mul_f32_e32 v250, 0xbfb8aa3b, v246
	v_exp_f32_e32 v247, v247
	v_exp_f32_e32 v248, v248
	v_exp_f32_e32 v249, v249
	v_exp_f32_e32 v250, v250
	s_nop 0
	v_add_f32_e32 v247, 1.0, v247
	v_add_f32_e32 v248, 1.0, v248
	v_add_f32_e32 v249, 1.0, v249
	v_add_f32_e32 v250, 1.0, v250
	v_rcp_f32_e32 v247, v247
	v_rcp_f32_e32 v248, v248
	v_rcp_f32_e32 v249, v249
	v_rcp_f32_e32 v250, v250
	s_nop 0
	v_mul_f32_e32 v243, v243, v247
	v_mul_f32_e32 v244, v244, v248
	v_mul_f32_e32 v245, v245, v249
	v_mul_f32_e32 v246, v246, v250
	v_mul_f32_e32 v12, v12, v243
	v_mul_f32_e32 v13, v13, v244
	v_mul_f32_e32 v14, v14, v245
	v_mul_f32_e32 v15, v15, v246
	v_cvt_pk_bf16_f32 v188, v12, v13
	v_cvt_pk_bf16_f32 v189, v14, v15
	global_store_dwordx2 v238, v[188:189], s[54:55] offset:48
	v_lshlrev_b32_e32 v243, 16, v190
	v_and_b32_e32 v244, 0xffff0000, v190
	v_lshlrev_b32_e32 v245, 16, v191
	v_and_b32_e32 v246, 0xffff0000, v191
	v_mul_f32_e32 v247, 0xbfb8aa3b, v243
	v_mul_f32_e32 v248, 0xbfb8aa3b, v244
	v_mul_f32_e32 v249, 0xbfb8aa3b, v245
	v_mul_f32_e32 v250, 0xbfb8aa3b, v246
	v_exp_f32_e32 v247, v247
	v_exp_f32_e32 v248, v248
	v_exp_f32_e32 v249, v249
	v_exp_f32_e32 v250, v250
	s_nop 0
	v_add_f32_e32 v247, 1.0, v247
	v_add_f32_e32 v248, 1.0, v248
	v_add_f32_e32 v249, 1.0, v249
	v_add_f32_e32 v250, 1.0, v250
	v_rcp_f32_e32 v247, v247
	v_rcp_f32_e32 v248, v248
	v_rcp_f32_e32 v249, v249
	v_rcp_f32_e32 v250, v250
	s_nop 0
	v_mul_f32_e32 v243, v243, v247
	v_mul_f32_e32 v244, v244, v248
	v_mul_f32_e32 v245, v245, v249
	v_mul_f32_e32 v246, v246, v250
	v_mul_f32_e32 v16, v16, v243
	v_mul_f32_e32 v17, v17, v244
	v_mul_f32_e32 v18, v18, v245
	v_mul_f32_e32 v19, v19, v246
	v_cvt_pk_bf16_f32 v190, v16, v17
	v_cvt_pk_bf16_f32 v191, v18, v19
	global_store_dwordx2 v238, v[190:191], s[54:55] offset:64
	v_lshlrev_b32_e32 v243, 16, v192
	v_and_b32_e32 v244, 0xffff0000, v192
	v_lshlrev_b32_e32 v245, 16, v193
	v_and_b32_e32 v246, 0xffff0000, v193
	v_mul_f32_e32 v247, 0xbfb8aa3b, v243
	v_mul_f32_e32 v248, 0xbfb8aa3b, v244
	v_mul_f32_e32 v249, 0xbfb8aa3b, v245
	v_mul_f32_e32 v250, 0xbfb8aa3b, v246
	v_exp_f32_e32 v247, v247
	v_exp_f32_e32 v248, v248
	v_exp_f32_e32 v249, v249
	v_exp_f32_e32 v250, v250
	s_nop 0
	v_add_f32_e32 v247, 1.0, v247
	v_add_f32_e32 v248, 1.0, v248
	v_add_f32_e32 v249, 1.0, v249
	v_add_f32_e32 v250, 1.0, v250
	v_rcp_f32_e32 v247, v247
	v_rcp_f32_e32 v248, v248
	v_rcp_f32_e32 v249, v249
	v_rcp_f32_e32 v250, v250
	s_nop 0
	v_mul_f32_e32 v243, v243, v247
	v_mul_f32_e32 v244, v244, v248
	v_mul_f32_e32 v245, v245, v249
	v_mul_f32_e32 v246, v246, v250
	v_mul_f32_e32 v20, v20, v243
	v_mul_f32_e32 v21, v21, v244
	v_mul_f32_e32 v22, v22, v245
	v_mul_f32_e32 v23, v23, v246
	v_cvt_pk_bf16_f32 v192, v20, v21
	v_cvt_pk_bf16_f32 v193, v22, v23
	global_store_dwordx2 v238, v[192:193], s[54:55] offset:80
	v_lshlrev_b32_e32 v243, 16, v194
	v_and_b32_e32 v244, 0xffff0000, v194
	v_lshlrev_b32_e32 v245, 16, v195
	v_and_b32_e32 v246, 0xffff0000, v195
	v_mul_f32_e32 v247, 0xbfb8aa3b, v243
	v_mul_f32_e32 v248, 0xbfb8aa3b, v244
	v_mul_f32_e32 v249, 0xbfb8aa3b, v245
	v_mul_f32_e32 v250, 0xbfb8aa3b, v246
	v_exp_f32_e32 v247, v247
	v_exp_f32_e32 v248, v248
	v_exp_f32_e32 v249, v249
	v_exp_f32_e32 v250, v250
	s_nop 0
	v_add_f32_e32 v247, 1.0, v247
	v_add_f32_e32 v248, 1.0, v248
	v_add_f32_e32 v249, 1.0, v249
	v_add_f32_e32 v250, 1.0, v250
	v_rcp_f32_e32 v247, v247
	v_rcp_f32_e32 v248, v248
	v_rcp_f32_e32 v249, v249
	v_rcp_f32_e32 v250, v250
	s_nop 0
	v_mul_f32_e32 v243, v243, v247
	v_mul_f32_e32 v244, v244, v248
	v_mul_f32_e32 v245, v245, v249
	v_mul_f32_e32 v246, v246, v250
	v_mul_f32_e32 v24, v24, v243
	v_mul_f32_e32 v25, v25, v244
	v_mul_f32_e32 v26, v26, v245
	v_mul_f32_e32 v27, v27, v246
	v_cvt_pk_bf16_f32 v194, v24, v25
	v_cvt_pk_bf16_f32 v195, v26, v27
	global_store_dwordx2 v238, v[194:195], s[54:55] offset:96
	v_lshlrev_b32_e32 v243, 16, v196
	v_and_b32_e32 v244, 0xffff0000, v196
	v_lshlrev_b32_e32 v245, 16, v197
	v_and_b32_e32 v246, 0xffff0000, v197
	v_mul_f32_e32 v247, 0xbfb8aa3b, v243
	v_mul_f32_e32 v248, 0xbfb8aa3b, v244
	v_mul_f32_e32 v249, 0xbfb8aa3b, v245
	v_mul_f32_e32 v250, 0xbfb8aa3b, v246
	v_exp_f32_e32 v247, v247
	v_exp_f32_e32 v248, v248
	v_exp_f32_e32 v249, v249
	v_exp_f32_e32 v250, v250
	s_nop 0
	v_add_f32_e32 v247, 1.0, v247
	v_add_f32_e32 v248, 1.0, v248
	v_add_f32_e32 v249, 1.0, v249
	v_add_f32_e32 v250, 1.0, v250
	v_rcp_f32_e32 v247, v247
	v_rcp_f32_e32 v248, v248
	v_rcp_f32_e32 v249, v249
	v_rcp_f32_e32 v250, v250
	s_nop 0
	v_mul_f32_e32 v243, v243, v247
	v_mul_f32_e32 v244, v244, v248
	v_mul_f32_e32 v245, v245, v249
	v_mul_f32_e32 v246, v246, v250
	v_mul_f32_e32 v28, v28, v243
	v_mul_f32_e32 v29, v29, v244
	v_mul_f32_e32 v30, v30, v245
	v_mul_f32_e32 v31, v31, v246
	v_cvt_pk_bf16_f32 v196, v28, v29
	v_cvt_pk_bf16_f32 v197, v30, v31
	global_store_dwordx2 v238, v[196:197], s[54:55] offset:112
	v_lshlrev_b32_e32 v243, 16, v198
	v_and_b32_e32 v244, 0xffff0000, v198
; DI unsigned pk2(float a, float b) { f32x2 v = {a, b}; bf16v2_t r = __builtin_convertvector(v, bf16v2_t); return __builtin_bit_cast(unsigned, r); }
; DI float silu(float x) { return x / (1.f + __expf(-x)); }
; DI void phase_attn_d(const Params& p, LAS unsigned char* lds) {
;     ...
; #pragma unroll
;             for (int dt = 0; dt < 4; ++dt)
; #pragma unroll
;                 for (int g4 = 0; g4 < 4; ++g4) { const int dv = 32 * dt + 8 * g4 + 4 * hh2;
;                     const u32x2 gw = *(const u32x2*)(gb + tokq2 * DM + h * 128 + dv);
;                     const float g0 = __uint_as_float(gw.x << 16), g1 = __uint_as_float(gw.x & 0xffff0000u), g2 = __uint_as_float(gw.y << 16), g3 = __uint_as_float(gw.y & 0xffff0000u);
;                     u32x2 w; w.x = pk2(O[dt][4 * g4] * silu(g0), O[dt][4 * g4 + 1] * silu(g1)); w.y = pk2(O[dt][4 * g4 + 2] * silu(g2), O[dt][4 * g4 + 3] * silu(g3));
;                     *(u32x2*)(y + tokq2 * DM + h * 128 + dv) = w; }
	v_lshlrev_b32_e32 v245, 16, v199
	v_and_b32_e32 v246, 0xffff0000, v199
	v_mul_f32_e32 v247, 0xbfb8aa3b, v243
	v_mul_f32_e32 v248, 0xbfb8aa3b, v244
	v_mul_f32_e32 v249, 0xbfb8aa3b, v245
	v_mul_f32_e32 v250, 0xbfb8aa3b, v246
	v_exp_f32_e32 v247, v247
	v_exp_f32_e32 v248, v248
	v_exp_f32_e32 v249, v249
	v_exp_f32_e32 v250, v250
	s_nop 0
	v_add_f32_e32 v247, 1.0, v247
	v_add_f32_e32 v248, 1.0, v248
	v_add_f32_e32 v249, 1.0, v249
	v_add_f32_e32 v250, 1.0, v250
	v_rcp_f32_e32 v247, v247
	v_rcp_f32_e32 v248, v248
	v_rcp_f32_e32 v249, v249
	v_rcp_f32_e32 v250, v250
	s_nop 0
	v_mul_f32_e32 v243, v243, v247
	v_mul_f32_e32 v244, v244, v248
	v_mul_f32_e32 v245, v245, v249
	v_mul_f32_e32 v246, v246, v250
	v_mul_f32_e32 v32, v32, v243
	v_mul_f32_e32 v33, v33, v244
	v_mul_f32_e32 v34, v34, v245
	v_mul_f32_e32 v35, v35, v246
	v_cvt_pk_bf16_f32 v198, v32, v33
	v_cvt_pk_bf16_f32 v199, v34, v35
	global_store_dwordx2 v238, v[198:199], s[54:55] offset:128
	v_lshlrev_b32_e32 v243, 16, v200
	v_and_b32_e32 v244, 0xffff0000, v200
	v_lshlrev_b32_e32 v245, 16, v201
	v_and_b32_e32 v246, 0xffff0000, v201
	v_mul_f32_e32 v247, 0xbfb8aa3b, v243
	v_mul_f32_e32 v248, 0xbfb8aa3b, v244
	v_mul_f32_e32 v249, 0xbfb8aa3b, v245
	v_mul_f32_e32 v250, 0xbfb8aa3b, v246
	v_exp_f32_e32 v247, v247
	v_exp_f32_e32 v248, v248
	v_exp_f32_e32 v249, v249
	v_exp_f32_e32 v250, v250
	s_nop 0
	v_add_f32_e32 v247, 1.0, v247
	v_add_f32_e32 v248, 1.0, v248
	v_add_f32_e32 v249, 1.0, v249
	v_add_f32_e32 v250, 1.0, v250
	v_rcp_f32_e32 v247, v247
	v_rcp_f32_e32 v248, v248
	v_rcp_f32_e32 v249, v249
	v_rcp_f32_e32 v250, v250
	s_nop 0
	v_mul_f32_e32 v243, v243, v247
	v_mul_f32_e32 v244, v244, v248
	v_mul_f32_e32 v245, v245, v249
	v_mul_f32_e32 v246, v246, v250
	v_mul_f32_e32 v36, v36, v243
	v_mul_f32_e32 v37, v37, v244
	v_mul_f32_e32 v38, v38, v245
	v_mul_f32_e32 v39, v39, v246
	v_cvt_pk_bf16_f32 v200, v36, v37
	v_cvt_pk_bf16_f32 v201, v38, v39
	global_store_dwordx2 v238, v[200:201], s[54:55] offset:144
	v_lshlrev_b32_e32 v243, 16, v202
	v_and_b32_e32 v244, 0xffff0000, v202
	v_lshlrev_b32_e32 v245, 16, v203
	v_and_b32_e32 v246, 0xffff0000, v203
	v_mul_f32_e32 v247, 0xbfb8aa3b, v243
	v_mul_f32_e32 v248, 0xbfb8aa3b, v244
	v_mul_f32_e32 v249, 0xbfb8aa3b, v245
	v_mul_f32_e32 v250, 0xbfb8aa3b, v246
	v_exp_f32_e32 v247, v247
	v_exp_f32_e32 v248, v248
	v_exp_f32_e32 v249, v249
	v_exp_f32_e32 v250, v250
	s_nop 0
	v_add_f32_e32 v247, 1.0, v247
	v_add_f32_e32 v248, 1.0, v248
	v_add_f32_e32 v249, 1.0, v249
	v_add_f32_e32 v250, 1.0, v250
	v_rcp_f32_e32 v247, v247
	v_rcp_f32_e32 v248, v248
	v_rcp_f32_e32 v249, v249
	v_rcp_f32_e32 v250, v250
	s_nop 0
	v_mul_f32_e32 v243, v243, v247
	v_mul_f32_e32 v244, v244, v248
	v_mul_f32_e32 v245, v245, v249
	v_mul_f32_e32 v246, v246, v250
	v_mul_f32_e32 v40, v40, v243
	v_mul_f32_e32 v41, v41, v244
	v_mul_f32_e32 v42, v42, v245
	v_mul_f32_e32 v43, v43, v246
	v_cvt_pk_bf16_f32 v202, v40, v41
	v_cvt_pk_bf16_f32 v203, v42, v43
	global_store_dwordx2 v238, v[202:203], s[54:55] offset:160
	v_lshlrev_b32_e32 v243, 16, v204
	v_and_b32_e32 v244, 0xffff0000, v204
	v_lshlrev_b32_e32 v245, 16, v205
	v_and_b32_e32 v246, 0xffff0000, v205
	v_mul_f32_e32 v247, 0xbfb8aa3b, v243
	v_mul_f32_e32 v248, 0xbfb8aa3b, v244
	v_mul_f32_e32 v249, 0xbfb8aa3b, v245
	v_mul_f32_e32 v250, 0xbfb8aa3b, v246
	v_exp_f32_e32 v247, v247
	v_exp_f32_e32 v248, v248
	v_exp_f32_e32 v249, v249
	v_exp_f32_e32 v250, v250
	s_nop 0
	v_add_f32_e32 v247, 1.0, v247
	v_add_f32_e32 v248, 1.0, v248
	v_add_f32_e32 v249, 1.0, v249
	v_add_f32_e32 v250, 1.0, v250
	v_rcp_f32_e32 v247, v247
	v_rcp_f32_e32 v248, v248
	v_rcp_f32_e32 v249, v249
	v_rcp_f32_e32 v250, v250
	s_nop 0
	v_mul_f32_e32 v243, v243, v247
	v_mul_f32_e32 v244, v244, v248
	v_mul_f32_e32 v245, v245, v249
	v_mul_f32_e32 v246, v246, v250
	v_mul_f32_e32 v44, v44, v243
	v_mul_f32_e32 v45, v45, v244
	v_mul_f32_e32 v46, v46, v245
	v_mul_f32_e32 v47, v47, v246
	v_cvt_pk_bf16_f32 v204, v44, v45
	v_cvt_pk_bf16_f32 v205, v46, v47
	global_store_dwordx2 v238, v[204:205], s[54:55] offset:176
	v_lshlrev_b32_e32 v243, 16, v206
	v_and_b32_e32 v244, 0xffff0000, v206
	v_lshlrev_b32_e32 v245, 16, v207
; DI unsigned pk2(float a, float b) { f32x2 v = {a, b}; bf16v2_t r = __builtin_convertvector(v, bf16v2_t); return __builtin_bit_cast(unsigned, r); }
; DI float silu(float x) { return x / (1.f + __expf(-x)); }
; DI void phase_attn_d(const Params& p, LAS unsigned char* lds) {
;     ...
;     for (int pr = blockIdx.x; pr < 512; pr += gridDim.x) {
;         const int bi = pr & 255, bh = (gridDim.x == 256) ? (bi & 7) + 8 * (bi >> 6) + 32 * (pr >> 8) : pr >> 3, j = (gridDim.x == 256) ? (bi >> 3) & 7 : pr & 7, b = bh >> 4, h = bh & 15;
;         for (int half = 0; half < 2; ++half) {
;             const int qb = half ? 15 - j : j;
;     ...
; #pragma unroll
;             for (int dt = 0; dt < 4; ++dt)
; #pragma unroll
;                 for (int g4 = 0; g4 < 4; ++g4) { const int dv = 32 * dt + 8 * g4 + 4 * hh2;
;                     const u32x2 gw = *(const u32x2*)(gb + tokq2 * DM + h * 128 + dv);
;                     const float g0 = __uint_as_float(gw.x << 16), g1 = __uint_as_float(gw.x & 0xffff0000u), g2 = __uint_as_float(gw.y << 16), g3 = __uint_as_float(gw.y & 0xffff0000u);
;                     u32x2 w; w.x = pk2(O[dt][4 * g4] * silu(g0), O[dt][4 * g4 + 1] * silu(g1)); w.y = pk2(O[dt][4 * g4 + 2] * silu(g2), O[dt][4 * g4 + 3] * silu(g3));
;                     *(u32x2*)(y + tokq2 * DM + h * 128 + dv) = w; }
	v_and_b32_e32 v246, 0xffff0000, v207
	v_mul_f32_e32 v247, 0xbfb8aa3b, v243
	v_mul_f32_e32 v248, 0xbfb8aa3b, v244
	v_mul_f32_e32 v249, 0xbfb8aa3b, v245
	v_mul_f32_e32 v250, 0xbfb8aa3b, v246
	v_exp_f32_e32 v247, v247
	v_exp_f32_e32 v248, v248
	v_exp_f32_e32 v249, v249
	v_exp_f32_e32 v250, v250
	s_nop 0
	v_add_f32_e32 v247, 1.0, v247
	v_add_f32_e32 v248, 1.0, v248
	v_add_f32_e32 v249, 1.0, v249
	v_add_f32_e32 v250, 1.0, v250
	v_rcp_f32_e32 v247, v247
	v_rcp_f32_e32 v248, v248
	v_rcp_f32_e32 v249, v249
	v_rcp_f32_e32 v250, v250
	s_nop 0
	v_mul_f32_e32 v243, v243, v247
	v_mul_f32_e32 v244, v244, v248
	v_mul_f32_e32 v245, v245, v249
	v_mul_f32_e32 v246, v246, v250
	v_mul_f32_e32 v48, v48, v243
	v_mul_f32_e32 v49, v49, v244
	v_mul_f32_e32 v50, v50, v245
	v_mul_f32_e32 v51, v51, v246
	v_cvt_pk_bf16_f32 v206, v48, v49
	v_cvt_pk_bf16_f32 v207, v50, v51
	global_store_dwordx2 v238, v[206:207], s[54:55] offset:192
	v_lshlrev_b32_e32 v243, 16, v208
	v_and_b32_e32 v244, 0xffff0000, v208
	v_lshlrev_b32_e32 v245, 16, v209
	v_and_b32_e32 v246, 0xffff0000, v209
	v_mul_f32_e32 v247, 0xbfb8aa3b, v243
	v_mul_f32_e32 v248, 0xbfb8aa3b, v244
	v_mul_f32_e32 v249, 0xbfb8aa3b, v245
	v_mul_f32_e32 v250, 0xbfb8aa3b, v246
	v_exp_f32_e32 v247, v247
	v_exp_f32_e32 v248, v248
	v_exp_f32_e32 v249, v249
	v_exp_f32_e32 v250, v250
	s_nop 0
	v_add_f32_e32 v247, 1.0, v247
	v_add_f32_e32 v248, 1.0, v248
	v_add_f32_e32 v249, 1.0, v249
	v_add_f32_e32 v250, 1.0, v250
	v_rcp_f32_e32 v247, v247
	v_rcp_f32_e32 v248, v248
	v_rcp_f32_e32 v249, v249
	v_rcp_f32_e32 v250, v250
	s_nop 0
	v_mul_f32_e32 v243, v243, v247
	v_mul_f32_e32 v244, v244, v248
	v_mul_f32_e32 v245, v245, v249
	v_mul_f32_e32 v246, v246, v250
	v_mul_f32_e32 v52, v52, v243
	v_mul_f32_e32 v53, v53, v244
	v_mul_f32_e32 v54, v54, v245
	v_mul_f32_e32 v55, v55, v246
	v_cvt_pk_bf16_f32 v208, v52, v53
	v_cvt_pk_bf16_f32 v209, v54, v55
	global_store_dwordx2 v238, v[208:209], s[54:55] offset:208
	v_lshlrev_b32_e32 v243, 16, v210
	v_and_b32_e32 v244, 0xffff0000, v210
	v_lshlrev_b32_e32 v245, 16, v211
	v_and_b32_e32 v246, 0xffff0000, v211
	v_mul_f32_e32 v247, 0xbfb8aa3b, v243
	v_mul_f32_e32 v248, 0xbfb8aa3b, v244
	v_mul_f32_e32 v249, 0xbfb8aa3b, v245
	v_mul_f32_e32 v250, 0xbfb8aa3b, v246
	v_exp_f32_e32 v247, v247
	v_exp_f32_e32 v248, v248
	v_exp_f32_e32 v249, v249
	v_exp_f32_e32 v250, v250
	s_nop 0
	v_add_f32_e32 v247, 1.0, v247
	v_add_f32_e32 v248, 1.0, v248
	v_add_f32_e32 v249, 1.0, v249
	v_add_f32_e32 v250, 1.0, v250
	v_rcp_f32_e32 v247, v247
	v_rcp_f32_e32 v248, v248
	v_rcp_f32_e32 v249, v249
	v_rcp_f32_e32 v250, v250
	s_nop 0
	v_mul_f32_e32 v243, v243, v247
	v_mul_f32_e32 v244, v244, v248
	v_mul_f32_e32 v245, v245, v249
	v_mul_f32_e32 v246, v246, v250
	v_mul_f32_e32 v56, v56, v243
	v_mul_f32_e32 v57, v57, v244
	v_mul_f32_e32 v58, v58, v245
	v_mul_f32_e32 v59, v59, v246
	v_cvt_pk_bf16_f32 v210, v56, v57
	v_cvt_pk_bf16_f32 v211, v58, v59
	global_store_dwordx2 v238, v[210:211], s[54:55] offset:224
	v_lshlrev_b32_e32 v243, 16, v212
	v_and_b32_e32 v244, 0xffff0000, v212
	v_lshlrev_b32_e32 v245, 16, v213
	v_and_b32_e32 v246, 0xffff0000, v213
	v_mul_f32_e32 v247, 0xbfb8aa3b, v243
	v_mul_f32_e32 v248, 0xbfb8aa3b, v244
	v_mul_f32_e32 v249, 0xbfb8aa3b, v245
	v_mul_f32_e32 v250, 0xbfb8aa3b, v246
	v_exp_f32_e32 v247, v247
	v_exp_f32_e32 v248, v248
	v_exp_f32_e32 v249, v249
	v_exp_f32_e32 v250, v250
	s_nop 0
	v_add_f32_e32 v247, 1.0, v247
	v_add_f32_e32 v248, 1.0, v248
	v_add_f32_e32 v249, 1.0, v249
	v_add_f32_e32 v250, 1.0, v250
	v_rcp_f32_e32 v247, v247
	v_rcp_f32_e32 v248, v248
	v_rcp_f32_e32 v249, v249
	v_rcp_f32_e32 v250, v250
	s_nop 0
	v_mul_f32_e32 v243, v243, v247
	v_mul_f32_e32 v244, v244, v248
	v_mul_f32_e32 v245, v245, v249
	v_mul_f32_e32 v246, v246, v250
	v_mul_f32_e32 v60, v60, v243
	v_mul_f32_e32 v61, v61, v244
	v_mul_f32_e32 v62, v62, v245
	v_mul_f32_e32 v63, v63, v246
	v_cvt_pk_bf16_f32 v212, v60, v61
	v_cvt_pk_bf16_f32 v213, v62, v63
	global_store_dwordx2 v238, v[212:213], s[54:55] offset:240
	s_cmp_eq_u32 s79, 0
	s_cbranch_scc1 .Lad_done
	s_mov_b32 s14, s88
	s_mov_b32 s15, s89
	s_mov_b32 s77, 0
	s_branch .Lad_half
